# removed the 20 mid-segment s_setprio 0/1 pairs inside the five GEMM K-loops (segment-level raise/lower kept); timing-only, outputs bit-identical
# speedup vs baseline: 1.0002x; 1.0002x over previous
; #define PG8_STAGE(bufoff, gbase, voff) do { _Pragma("unroll") for (int _i = 0; _i < 2; ++_i) \
;         __builtin_amdgcn_global_load_lds((const unsigned*)((const char*)(gbase) + (voff)[_i]), (PG8_LAS unsigned*)(lds + (bufoff) + ldsw + _i * 8192), 16, 0, 0); } while (0)
; #define PG8_LDA(dst, b, h) do { _Pragma("unroll") for (int m = 0; m < 4; ++m) _Pragma("unroll") for (int k = 0; k < 2; ++k) dst[m][k] = *(const PG8_LAS bf16x8*)(lds + PG8_SA(b, h) + aoff + m * 2048 + k * 1024); } while (0)
; #define PG8_LDB(dst, b, h) do { _Pragma("unroll") for (int n = 0; n < 2; ++n) _Pragma("unroll") for (int k = 0; k < 2; ++k) dst[n][k] = *(const PG8_LAS bf16x8*)(lds + PG8_SB(b, h) + boff + n * 2048 + k * 1024); } while (0)
; #define PG8_MMA(ai, bj, At, Bt) do { __builtin_amdgcn_s_setprio(1); _Pragma("unroll") for (int m = 0; m < 4; ++m) _Pragma("unroll") for (int n = 0; n < 2; ++n) _Pragma("unroll") for (int k = 0; k < 2; ++k) \
;         acc[ai][bj][m][n] = __builtin_amdgcn_mfma_f32_16x16x32_bf16(Bt[n][k], At[m][k], acc[ai][bj][m][n], 0, 0, 0); __builtin_amdgcn_s_setprio(0); } while (0)
; #define PG8_WAIT_V(n) asm volatile("s_waitcnt vmcnt(" #n ")" ::: "memory")
; #define PG8_WAIT_L(n) asm volatile("s_waitcnt lgkmcnt(" #n ")" ::: "memory")
; #define PG8_BAR __builtin_amdgcn_s_barrier()
; #define PG8_SCHED __builtin_amdgcn_sched_barrier(0)
; template <class Epi, class Sched, bool ALIGN_EPI = false, bool SP2 = false>
; __device__ __forceinline__ void gemm_phase(PG8_LAS unsigned char* lds, const Gemm g, const Sched& S, const Epi& E) {
;     ...
;             const bool last = (t == nt - 2);
;             const char* a1 = cA + (size_t)(t + 1) * kstep;
;             const char* a2 = last ? nA : cA + (size_t)(t + 2) * kstep; const char* b2 = last ? nB : cB + (size_t)(t + 2) * kstep;
;             const char* a3 = a2 + kstep; const char* b3 = b2 + kstep;
;             if (last && has_next) S.a_ready(nxt);
;             if constexpr (SP2) {
;             PG8_LDB(B0, 0, 0); PG8_LDB(B1, 0, 1); PG8_SCHED; PG8_LDA(At, 0, 0); PG8_STAGE(PG8_SA(1, 1), a1 + hstep, voffA);
;             PG8_WAIT_V(8); PG8_WAIT_L(0); PG8_BAR; PG8_MMA(0, 0, At, B0); PG8_MMA(0, 1, At, B1); PG8_BAR; PG8_SCHED;
;             PG8_LDA(At, 0, 1); PG8_STAGE(PG8_SB(0, 0), b2, voffB); PG8_STAGE(PG8_SB(0, 1), b2 + hstep, voffB); PG8_STAGE(PG8_SA(0, 0), a2, voffA);
.LBB0_183:
	ds_read_b128 v[144:147], v186
	ds_read_b128 v[148:151], v186 offset:1024
	ds_read_b128 v[152:155], v186 offset:2048
	ds_read_b128 v[156:159], v186 offset:3072
	ds_read_b128 v[160:163], v187
	ds_read_b128 v[164:167], v187 offset:1024
	ds_read_b128 v[168:171], v187 offset:2048
	ds_read_b128 v[172:175], v187 offset:3072
	s_add_u32 s8, s6, 0xfff00080
	s_addc_u32 s9, s7, -1
	s_cmp_eq_u32 s17, 60
	s_cselect_b32 s11, s1, s9
	s_cselect_b32 s10, s12, s8
	s_cselect_b32 s9, s13, s16
	s_cselect_b32 s8, s14, s15
	v_lshl_add_u64 v[214:215], s[6:7], 0, v[140:141]
	s_add_i32 m0, s41, 0xc000
	s_waitcnt lgkmcnt(0)
	ds_read_b128 v[176:179], v188
	ds_read_b128 v[190:193], v188 offset:1024
	ds_read_b128 v[194:197], v188 offset:2048
	ds_read_b128 v[198:201], v188 offset:3072
	ds_read_b128 v[202:205], v188 offset:4096
	ds_read_b128 v[206:209], v188 offset:5120
	ds_read_b128 v[210:213], v188 offset:6144
	ds_read_b128 v[218:221], v188 offset:7168
	global_load_lds_dwordx4 v[214:215], off
	v_lshl_add_u64 v[214:215], s[6:7], 0, v[142:143]
	s_add_i32 m0, s41, 0xe000
	s_nop 0
	global_load_lds_dwordx4 v[214:215], off
	s_waitcnt vmcnt(8)
	s_waitcnt lgkmcnt(0)
	s_barrier
	s_setprio 1
	s_waitcnt lgkmcnt(0)
	v_mfma_f32_16x16x32_bf16 v[126:129], v[144:147], v[176:179], v[126:129]
	v_mfma_f32_16x16x32_bf16 v[122:125], v[152:155], v[176:179], v[122:125]
	v_mfma_f32_16x16x32_bf16 v[114:117], v[144:147], v[194:197], v[114:117]
	v_mfma_f32_16x16x32_bf16 v[106:109], v[152:155], v[194:197], v[106:109]
	v_mfma_f32_16x16x32_bf16 v[98:101], v[144:147], v[202:205], v[98:101]
	v_mfma_f32_16x16x32_bf16 v[90:93], v[152:155], v[202:205], v[90:93]
	v_mfma_f32_16x16x32_bf16 v[82:85], v[144:147], v[210:213], v[82:85]
	v_mfma_f32_16x16x32_bf16 v[74:77], v[152:155], v[210:213], v[74:77]
	v_mfma_f32_16x16x32_bf16 v[126:129], v[148:151], v[190:193], v[126:129]
	v_mfma_f32_16x16x32_bf16 v[122:125], v[156:159], v[190:193], v[122:125]
	v_mfma_f32_16x16x32_bf16 v[114:117], v[148:151], v[198:201], v[114:117]
	v_mfma_f32_16x16x32_bf16 v[106:109], v[156:159], v[198:201], v[106:109]
	v_mfma_f32_16x16x32_bf16 v[98:101], v[148:151], v[206:209], v[98:101]
	v_mfma_f32_16x16x32_bf16 v[90:93], v[156:159], v[206:209], v[90:93]
	v_mfma_f32_16x16x32_bf16 v[82:85], v[148:151], v[218:221], v[82:85]
	v_mfma_f32_16x16x32_bf16 v[74:77], v[156:159], v[218:221], v[74:77]
	v_mfma_f32_16x16x32_bf16 v[118:121], v[160:163], v[176:179], v[118:121]
	v_mfma_f32_16x16x32_bf16 v[110:113], v[168:171], v[176:179], v[110:113]
	v_mfma_f32_16x16x32_bf16 v[102:105], v[160:163], v[194:197], v[102:105]
	v_mfma_f32_16x16x32_bf16 v[94:97], v[168:171], v[194:197], v[94:97]
	v_mfma_f32_16x16x32_bf16 v[86:89], v[160:163], v[202:205], v[86:89]
	v_mfma_f32_16x16x32_bf16 v[78:81], v[168:171], v[202:205], v[78:81]
	v_mfma_f32_16x16x32_bf16 v[70:73], v[160:163], v[210:213], v[70:73]
	v_mfma_f32_16x16x32_bf16 v[66:69], v[168:171], v[210:213], v[66:69]
	v_mfma_f32_16x16x32_bf16 v[118:121], v[164:167], v[190:193], v[118:121]
	v_mfma_f32_16x16x32_bf16 v[110:113], v[172:175], v[190:193], v[110:113]
	v_mfma_f32_16x16x32_bf16 v[102:105], v[164:167], v[198:201], v[102:105]
	v_mfma_f32_16x16x32_bf16 v[94:97], v[172:175], v[198:201], v[94:97]
	v_mfma_f32_16x16x32_bf16 v[86:89], v[164:167], v[206:209], v[86:89]
	v_mfma_f32_16x16x32_bf16 v[78:81], v[172:175], v[206:209], v[78:81]
	v_mfma_f32_16x16x32_bf16 v[70:73], v[164:167], v[218:221], v[70:73]
	v_mfma_f32_16x16x32_bf16 v[66:69], v[172:175], v[218:221], v[66:69]
	s_setprio 0
	s_barrier
	s_add_i32 s18, s62, s5
	v_lshl_add_u64 v[214:215], s[8:9], 0, v[132:133]
	s_mov_b32 m0, s18
	ds_read_b128 v[176:179], v188 offset:16384
	ds_read_b128 v[190:193], v188 offset:17408
	ds_read_b128 v[194:197], v188 offset:18432
	ds_read_b128 v[198:201], v188 offset:19456
	ds_read_b128 v[202:205], v188 offset:20480
	ds_read_b128 v[206:209], v188 offset:21504
	ds_read_b128 v[210:213], v188 offset:22528
	ds_read_b128 v[218:221], v188 offset:23552
	global_load_lds_dwordx4 v[214:215], off
	s_add_i32 m0, s18, 0x2000
	s_add_u32 s18, s8, 0x100000
	v_lshl_add_u64 v[222:223], s[8:9], 0, v[136:137]
	s_addc_u32 s19, s9, 0
	s_add_i32 s20, s63, s5
	global_load_lds_dwordx4 v[222:223], off
	v_lshl_add_u64 v[224:225], s[18:19], 0, v[132:133]
	s_mov_b32 m0, s20
	v_lshl_add_u64 v[226:227], s[10:11], 0, v[134:135]
	global_load_lds_dwordx4 v[224:225], off
	v_lshl_add_u64 v[224:225], s[18:19], 0, v[136:137]
	s_add_i32 m0, s20, 0x2000
	s_nop 0
	global_load_lds_dwordx4 v[224:225], off
	v_lshl_add_u64 v[224:225], s[10:11], 0, v[130:131]
	s_mov_b32 m0, s41
	s_nop 0
	global_load_lds_dwordx4 v[224:225], off
	s_mov_b32 m0, s43
	s_nop 0
	global_load_lds_dwordx4 v[226:227], off
	s_waitcnt vmcnt(8)
	s_waitcnt lgkmcnt(0)
	s_barrier
; #define PG8_STAGE(bufoff, gbase, voff) do { _Pragma("unroll") for (int _i = 0; _i < 2; ++_i) \
;         __builtin_amdgcn_global_load_lds((const unsigned*)((const char*)(gbase) + (voff)[_i]), (PG8_LAS unsigned*)(lds + (bufoff) + ldsw + _i * 8192), 16, 0, 0); } while (0)
; #define PG8_LDA(dst, b, h) do { _Pragma("unroll") for (int m = 0; m < 4; ++m) _Pragma("unroll") for (int k = 0; k < 2; ++k) dst[m][k] = *(const PG8_LAS bf16x8*)(lds + PG8_SA(b, h) + aoff + m * 2048 + k * 1024); } while (0)
; #define PG8_LDB(dst, b, h) do { _Pragma("unroll") for (int n = 0; n < 2; ++n) _Pragma("unroll") for (int k = 0; k < 2; ++k) dst[n][k] = *(const PG8_LAS bf16x8*)(lds + PG8_SB(b, h) + boff + n * 2048 + k * 1024); } while (0)
; #define PG8_MMA(ai, bj, At, Bt) do { __builtin_amdgcn_s_setprio(1); _Pragma("unroll") for (int m = 0; m < 4; ++m) _Pragma("unroll") for (int n = 0; n < 2; ++n) _Pragma("unroll") for (int k = 0; k < 2; ++k) \
;         acc[ai][bj][m][n] = __builtin_amdgcn_mfma_f32_16x16x32_bf16(Bt[n][k], At[m][k], acc[ai][bj][m][n], 0, 0, 0); __builtin_amdgcn_s_setprio(0); } while (0)
; #define PG8_WAIT_V(n) asm volatile("s_waitcnt vmcnt(" #n ")" ::: "memory")
; #define PG8_WAIT_L(n) asm volatile("s_waitcnt lgkmcnt(" #n ")" ::: "memory")
; #define PG8_BAR __builtin_amdgcn_s_barrier()
; #define PG8_SCHED __builtin_amdgcn_sched_barrier(0)
; template <class Epi, class Sched, bool ALIGN_EPI = false, bool SP2 = false>
; __device__ __forceinline__ void gemm_phase(PG8_LAS unsigned char* lds, const Gemm g, const Sched& S, const Epi& E) {
;     ...
;             PG8_WAIT_V(8); PG8_WAIT_L(0); PG8_BAR; PG8_MMA(1, 0, At, B0); PG8_MMA(1, 1, At, B1); PG8_BAR; PG8_SCHED;
;             PG8_LDB(B0, 1, 0); PG8_LDB(B1, 1, 1); PG8_SCHED; PG8_LDA(At, 1, 0); PG8_STAGE(PG8_SA(0, 1), a2 + hstep, voffA);
;             PG8_WAIT_V(8); PG8_WAIT_L(0); PG8_BAR; PG8_MMA(0, 0, At, B0); PG8_MMA(0, 1, At, B1); PG8_BAR; PG8_SCHED;
	s_setprio 1
	s_waitcnt lgkmcnt(0)
	v_mfma_f32_16x16x32_bf16 v[62:65], v[144:147], v[176:179], v[62:65]
	v_mfma_f32_16x16x32_bf16 v[58:61], v[152:155], v[176:179], v[58:61]
	v_mfma_f32_16x16x32_bf16 v[50:53], v[144:147], v[194:197], v[50:53]
	v_mfma_f32_16x16x32_bf16 v[42:45], v[152:155], v[194:197], v[42:45]
	v_mfma_f32_16x16x32_bf16 v[34:37], v[144:147], v[202:205], v[34:37]
	v_mfma_f32_16x16x32_bf16 v[26:29], v[152:155], v[202:205], v[26:29]
	v_mfma_f32_16x16x32_bf16 v[18:21], v[144:147], v[210:213], v[18:21]
	v_mfma_f32_16x16x32_bf16 v[10:13], v[152:155], v[210:213], v[10:13]
	v_mfma_f32_16x16x32_bf16 v[62:65], v[148:151], v[190:193], v[62:65]
	v_mfma_f32_16x16x32_bf16 v[58:61], v[156:159], v[190:193], v[58:61]
	v_mfma_f32_16x16x32_bf16 v[50:53], v[148:151], v[198:201], v[50:53]
	v_mfma_f32_16x16x32_bf16 v[42:45], v[156:159], v[198:201], v[42:45]
	v_mfma_f32_16x16x32_bf16 v[34:37], v[148:151], v[206:209], v[34:37]
	v_mfma_f32_16x16x32_bf16 v[26:29], v[156:159], v[206:209], v[26:29]
	v_mfma_f32_16x16x32_bf16 v[18:21], v[148:151], v[218:221], v[18:21]
	v_mfma_f32_16x16x32_bf16 v[10:13], v[156:159], v[218:221], v[10:13]
	v_mfma_f32_16x16x32_bf16 v[54:57], v[160:163], v[176:179], v[54:57]
	v_mfma_f32_16x16x32_bf16 v[46:49], v[168:171], v[176:179], v[46:49]
	v_mfma_f32_16x16x32_bf16 v[38:41], v[160:163], v[194:197], v[38:41]
	v_mfma_f32_16x16x32_bf16 v[30:33], v[168:171], v[194:197], v[30:33]
	v_mfma_f32_16x16x32_bf16 v[22:25], v[160:163], v[202:205], v[22:25]
	v_mfma_f32_16x16x32_bf16 v[14:17], v[168:171], v[202:205], v[14:17]
	v_mfma_f32_16x16x32_bf16 v[6:9], v[160:163], v[210:213], v[6:9]
	v_mfma_f32_16x16x32_bf16 v[2:5], v[168:171], v[210:213], v[2:5]
	v_mfma_f32_16x16x32_bf16 v[54:57], v[164:167], v[190:193], v[54:57]
	v_mfma_f32_16x16x32_bf16 v[46:49], v[172:175], v[190:193], v[46:49]
	v_mfma_f32_16x16x32_bf16 v[38:41], v[164:167], v[198:201], v[38:41]
	v_mfma_f32_16x16x32_bf16 v[30:33], v[172:175], v[198:201], v[30:33]
	v_mfma_f32_16x16x32_bf16 v[22:25], v[164:167], v[206:209], v[22:25]
	v_mfma_f32_16x16x32_bf16 v[14:17], v[172:175], v[206:209], v[14:17]
	v_mfma_f32_16x16x32_bf16 v[6:9], v[164:167], v[218:221], v[6:9]
	v_mfma_f32_16x16x32_bf16 v[2:5], v[172:175], v[218:221], v[2:5]
	s_setprio 0
	s_barrier
	s_add_i32 s18, 0, 0x18000
	v_add_u32_e32 v139, s18, v180
	s_add_i32 s19, 0, 0x1c000
	ds_read_b128 v[144:147], v139
	ds_read_b128 v[148:151], v139 offset:1024
	ds_read_b128 v[152:155], v139 offset:2048
	ds_read_b128 v[156:159], v139 offset:3072
	v_add_u32_e32 v139, s19, v180
	ds_read_b128 v[160:163], v139
	ds_read_b128 v[164:167], v139 offset:1024
	ds_read_b128 v[168:171], v139 offset:2048
	ds_read_b128 v[172:175], v139 offset:3072
	s_add_u32 s10, s10, 0x100000
	s_addc_u32 s11, s11, 0
	s_mov_b32 m0, s45
	v_lshl_add_u64 v[228:229], s[10:11], 0, v[130:131]
	ds_read_b128 v[176:179], v188 offset:32768
	ds_read_b128 v[190:193], v188 offset:33792
	ds_read_b128 v[194:197], v188 offset:34816
	ds_read_b128 v[198:201], v188 offset:35840
	ds_read_b128 v[202:205], v188 offset:36864
	ds_read_b128 v[206:209], v188 offset:37888
	ds_read_b128 v[210:213], v188 offset:38912
	ds_read_b128 v[218:221], v188 offset:39936
	global_load_lds_dwordx4 v[228:229], off
	v_lshl_add_u64 v[228:229], s[10:11], 0, v[134:135]
	s_mov_b32 m0, s47
	s_nop 0
	global_load_lds_dwordx4 v[228:229], off
	s_waitcnt vmcnt(8)
	s_waitcnt lgkmcnt(0)
	s_barrier
	s_setprio 1
	s_waitcnt lgkmcnt(0)
	v_mfma_f32_16x16x32_bf16 v[126:129], v[144:147], v[176:179], v[126:129]
	v_mfma_f32_16x16x32_bf16 v[122:125], v[152:155], v[176:179], v[122:125]
	v_mfma_f32_16x16x32_bf16 v[114:117], v[144:147], v[194:197], v[114:117]
	v_mfma_f32_16x16x32_bf16 v[106:109], v[152:155], v[194:197], v[106:109]
	v_mfma_f32_16x16x32_bf16 v[98:101], v[144:147], v[202:205], v[98:101]
	v_mfma_f32_16x16x32_bf16 v[90:93], v[152:155], v[202:205], v[90:93]
	v_mfma_f32_16x16x32_bf16 v[82:85], v[144:147], v[210:213], v[82:85]
	v_mfma_f32_16x16x32_bf16 v[74:77], v[152:155], v[210:213], v[74:77]
	v_mfma_f32_16x16x32_bf16 v[126:129], v[148:151], v[190:193], v[126:129]
	v_mfma_f32_16x16x32_bf16 v[122:125], v[156:159], v[190:193], v[122:125]
	v_mfma_f32_16x16x32_bf16 v[114:117], v[148:151], v[198:201], v[114:117]
	v_mfma_f32_16x16x32_bf16 v[106:109], v[156:159], v[198:201], v[106:109]
	v_mfma_f32_16x16x32_bf16 v[98:101], v[148:151], v[206:209], v[98:101]
	v_mfma_f32_16x16x32_bf16 v[90:93], v[156:159], v[206:209], v[90:93]
	v_mfma_f32_16x16x32_bf16 v[82:85], v[148:151], v[218:221], v[82:85]
	v_mfma_f32_16x16x32_bf16 v[74:77], v[156:159], v[218:221], v[74:77]
	v_mfma_f32_16x16x32_bf16 v[118:121], v[160:163], v[176:179], v[118:121]
	v_mfma_f32_16x16x32_bf16 v[110:113], v[168:171], v[176:179], v[110:113]
	v_mfma_f32_16x16x32_bf16 v[102:105], v[160:163], v[194:197], v[102:105]
	v_mfma_f32_16x16x32_bf16 v[94:97], v[168:171], v[194:197], v[94:97]
	v_mfma_f32_16x16x32_bf16 v[86:89], v[160:163], v[202:205], v[86:89]
	v_mfma_f32_16x16x32_bf16 v[78:81], v[168:171], v[202:205], v[78:81]
	v_mfma_f32_16x16x32_bf16 v[70:73], v[160:163], v[210:213], v[70:73]
	v_mfma_f32_16x16x32_bf16 v[66:69], v[168:171], v[210:213], v[66:69]
	v_mfma_f32_16x16x32_bf16 v[118:121], v[164:167], v[190:193], v[118:121]
	v_mfma_f32_16x16x32_bf16 v[110:113], v[172:175], v[190:193], v[110:113]
	v_mfma_f32_16x16x32_bf16 v[102:105], v[164:167], v[198:201], v[102:105]
	v_mfma_f32_16x16x32_bf16 v[94:97], v[172:175], v[198:201], v[94:97]
	v_mfma_f32_16x16x32_bf16 v[86:89], v[164:167], v[206:209], v[86:89]
	v_mfma_f32_16x16x32_bf16 v[78:81], v[172:175], v[206:209], v[78:81]
	v_mfma_f32_16x16x32_bf16 v[70:73], v[164:167], v[218:221], v[70:73]
	v_mfma_f32_16x16x32_bf16 v[66:69], v[172:175], v[218:221], v[66:69]
	s_setprio 0
	s_barrier
; #define PG8_STAGE(bufoff, gbase, voff) do { _Pragma("unroll") for (int _i = 0; _i < 2; ++_i) \
;         __builtin_amdgcn_global_load_lds((const unsigned*)((const char*)(gbase) + (voff)[_i]), (PG8_LAS unsigned*)(lds + (bufoff) + ldsw + _i * 8192), 16, 0, 0); } while (0)
; #define PG8_LDA(dst, b, h) do { _Pragma("unroll") for (int m = 0; m < 4; ++m) _Pragma("unroll") for (int k = 0; k < 2; ++k) dst[m][k] = *(const PG8_LAS bf16x8*)(lds + PG8_SA(b, h) + aoff + m * 2048 + k * 1024); } while (0)
; #define PG8_MMA(ai, bj, At, Bt) do { __builtin_amdgcn_s_setprio(1); _Pragma("unroll") for (int m = 0; m < 4; ++m) _Pragma("unroll") for (int n = 0; n < 2; ++n) _Pragma("unroll") for (int k = 0; k < 2; ++k) \
;         acc[ai][bj][m][n] = __builtin_amdgcn_mfma_f32_16x16x32_bf16(Bt[n][k], At[m][k], acc[ai][bj][m][n], 0, 0, 0); __builtin_amdgcn_s_setprio(0); } while (0)
; #define PG8_WAIT_V(n) asm volatile("s_waitcnt vmcnt(" #n ")" ::: "memory")
; #define PG8_WAIT_L(n) asm volatile("s_waitcnt lgkmcnt(" #n ")" ::: "memory")
; #define PG8_BAR __builtin_amdgcn_s_barrier()
; #define PG8_SCHED __builtin_amdgcn_sched_barrier(0)
; template <class Epi, class Sched, bool ALIGN_EPI = false, bool SP2 = false>
; __device__ __forceinline__ void gemm_phase(PG8_LAS unsigned char* lds, const Gemm g, const Sched& S, const Epi& E) {
;     ...
;             PG8_LDA(At, 1, 1); PG8_STAGE(PG8_SB(1, 0), b3, voffB); PG8_STAGE(PG8_SB(1, 1), b3 + hstep, voffB); PG8_STAGE(PG8_SA(1, 0), a3, voffA);
;             PG8_WAIT_V(8); PG8_WAIT_L(0); PG8_BAR; PG8_MMA(1, 0, At, B0); PG8_MMA(1, 1, At, B1); PG8_BAR; PG8_SCHED;
;     ...
;         if constexpr (ALIGN_EPI) { if (wr == 0) PG8_BAR; }
;         if constexpr (!Epi::AFTER_DRAIN) { E(acc, cur, wr, wc, fr, fq); S.done(cur); }
;         if (!has_next) break;
	s_add_i32 s10, s18, s5
	v_lshl_add_u64 v[214:215], v[214:215], 0, s[50:51]
	s_mov_b32 m0, s10
	ds_read_b128 v[176:179], v188 offset:49152
	ds_read_b128 v[190:193], v188 offset:50176
	ds_read_b128 v[194:197], v188 offset:51200
	ds_read_b128 v[198:201], v188 offset:52224
	ds_read_b128 v[202:205], v188 offset:53248
	ds_read_b128 v[206:209], v188 offset:54272
	ds_read_b128 v[210:213], v188 offset:55296
	ds_read_b128 v[218:221], v188 offset:56320
	global_load_lds_dwordx4 v[214:215], off
	s_add_i32 m0, s10, 0x2000
	s_add_u32 s8, s8, 0x100080
	v_lshl_add_u64 v[214:215], v[222:223], 0, s[50:51]
	s_addc_u32 s9, s9, 0
	s_add_i32 s10, s19, s5
	global_load_lds_dwordx4 v[214:215], off
	v_lshl_add_u64 v[214:215], s[8:9], 0, v[132:133]
	s_mov_b32 m0, s10
	s_nop 0
	global_load_lds_dwordx4 v[214:215], off
	v_lshl_add_u64 v[214:215], s[8:9], 0, v[136:137]
	s_add_i32 m0, s10, 0x2000
	s_nop 0
	global_load_lds_dwordx4 v[214:215], off
	v_lshl_add_u64 v[214:215], v[224:225], 0, s[50:51]
	s_mov_b32 m0, s55
	s_nop 0
	global_load_lds_dwordx4 v[214:215], off
	v_lshl_add_u64 v[214:215], v[226:227], 0, s[50:51]
	s_mov_b32 m0, s57
	s_nop 0
	global_load_lds_dwordx4 v[214:215], off
	s_waitcnt vmcnt(8)
	s_waitcnt lgkmcnt(0)
	s_barrier
	s_setprio 1
	s_waitcnt lgkmcnt(0)
	v_mfma_f32_16x16x32_bf16 v[62:65], v[144:147], v[176:179], v[62:65]
	v_mfma_f32_16x16x32_bf16 v[58:61], v[152:155], v[176:179], v[58:61]
	v_mfma_f32_16x16x32_bf16 v[50:53], v[144:147], v[194:197], v[50:53]
	v_mfma_f32_16x16x32_bf16 v[42:45], v[152:155], v[194:197], v[42:45]
	v_mfma_f32_16x16x32_bf16 v[34:37], v[144:147], v[202:205], v[34:37]
	v_mfma_f32_16x16x32_bf16 v[26:29], v[152:155], v[202:205], v[26:29]
	v_mfma_f32_16x16x32_bf16 v[18:21], v[144:147], v[210:213], v[18:21]
	v_mfma_f32_16x16x32_bf16 v[10:13], v[152:155], v[210:213], v[10:13]
	v_mfma_f32_16x16x32_bf16 v[62:65], v[148:151], v[190:193], v[62:65]
	v_mfma_f32_16x16x32_bf16 v[58:61], v[156:159], v[190:193], v[58:61]
	v_mfma_f32_16x16x32_bf16 v[50:53], v[148:151], v[198:201], v[50:53]
	v_mfma_f32_16x16x32_bf16 v[42:45], v[156:159], v[198:201], v[42:45]
	v_mfma_f32_16x16x32_bf16 v[34:37], v[148:151], v[206:209], v[34:37]
	v_mfma_f32_16x16x32_bf16 v[26:29], v[156:159], v[206:209], v[26:29]
	v_mfma_f32_16x16x32_bf16 v[18:21], v[148:151], v[218:221], v[18:21]
	v_mfma_f32_16x16x32_bf16 v[10:13], v[156:159], v[218:221], v[10:13]
	v_mfma_f32_16x16x32_bf16 v[54:57], v[160:163], v[176:179], v[54:57]
	v_mfma_f32_16x16x32_bf16 v[46:49], v[168:171], v[176:179], v[46:49]
	v_mfma_f32_16x16x32_bf16 v[38:41], v[160:163], v[194:197], v[38:41]
	v_mfma_f32_16x16x32_bf16 v[30:33], v[168:171], v[194:197], v[30:33]
	v_mfma_f32_16x16x32_bf16 v[22:25], v[160:163], v[202:205], v[22:25]
	v_mfma_f32_16x16x32_bf16 v[14:17], v[168:171], v[202:205], v[14:17]
	v_mfma_f32_16x16x32_bf16 v[6:9], v[160:163], v[210:213], v[6:9]
	v_mfma_f32_16x16x32_bf16 v[2:5], v[168:171], v[210:213], v[2:5]
	v_mfma_f32_16x16x32_bf16 v[54:57], v[164:167], v[190:193], v[54:57]
	v_mfma_f32_16x16x32_bf16 v[46:49], v[172:175], v[190:193], v[46:49]
	v_mfma_f32_16x16x32_bf16 v[38:41], v[164:167], v[198:201], v[38:41]
	v_mfma_f32_16x16x32_bf16 v[30:33], v[172:175], v[198:201], v[30:33]
	v_mfma_f32_16x16x32_bf16 v[22:25], v[164:167], v[206:209], v[22:25]
	v_mfma_f32_16x16x32_bf16 v[14:17], v[172:175], v[206:209], v[14:17]
	v_mfma_f32_16x16x32_bf16 v[6:9], v[164:167], v[218:221], v[6:9]
	v_mfma_f32_16x16x32_bf16 v[2:5], v[172:175], v[218:221], v[2:5]
	s_setprio 0
	s_barrier
	s_add_i32 s17, s17, 2
	s_add_u32 s6, s6, 0x100
	s_addc_u32 s7, s7, 0
	s_add_u32 s15, s15, 0x100
	s_addc_u32 s16, s16, 0
	s_cmp_gt_u32 s17, 61
	s_cbranch_scc0 .LBB0_183
	s_and_b64 vcc, exec, s[22:23]
	s_cbranch_vccnz .LBB0_188
	v_lshl_add_u32 v144, s0, 8, v1
	s_cmp_gt_i32 s40, 3
	s_mov_b64 s[0:1], -1
	s_cbranch_scc1 .LBB0_189

; #define PG8_STAGE(bufoff, gbase, voff) do { _Pragma("unroll") for (int _i = 0; _i < 2; ++_i) \
;         __builtin_amdgcn_global_load_lds((const unsigned*)((const char*)(gbase) + (voff)[_i]), (PG8_LAS unsigned*)(lds + (bufoff) + ldsw + _i * 8192), 16, 0, 0); } while (0)
; #define PG8_LDA(dst, b, h) do { _Pragma("unroll") for (int m = 0; m < 4; ++m) _Pragma("unroll") for (int k = 0; k < 2; ++k) dst[m][k] = *(const PG8_LAS bf16x8*)(lds + PG8_SA(b, h) + aoff + m * 2048 + k * 1024); } while (0)
; #define PG8_LDB(dst, b, h) do { _Pragma("unroll") for (int n = 0; n < 2; ++n) _Pragma("unroll") for (int k = 0; k < 2; ++k) dst[n][k] = *(const PG8_LAS bf16x8*)(lds + PG8_SB(b, h) + boff + n * 2048 + k * 1024); } while (0)
; #define PG8_MMA(ai, bj, At, Bt) do { __builtin_amdgcn_s_setprio(1); _Pragma("unroll") for (int m = 0; m < 4; ++m) _Pragma("unroll") for (int n = 0; n < 2; ++n) _Pragma("unroll") for (int k = 0; k < 2; ++k) \
;         acc[ai][bj][m][n] = __builtin_amdgcn_mfma_f32_16x16x32_bf16(Bt[n][k], At[m][k], acc[ai][bj][m][n], 0, 0, 0); __builtin_amdgcn_s_setprio(0); } while (0)
; #define PG8_WAIT_V(n) asm volatile("s_waitcnt vmcnt(" #n ")" ::: "memory")
; #define PG8_WAIT_L(n) asm volatile("s_waitcnt lgkmcnt(" #n ")" ::: "memory")
; #define PG8_BAR __builtin_amdgcn_s_barrier()
; #define PG8_SCHED __builtin_amdgcn_sched_barrier(0)
; template <class Epi, class Sched, bool ALIGN_EPI = false, bool SP2 = false>
; __device__ __forceinline__ void gemm_phase(PG8_LAS unsigned char* lds, const Gemm g, const Sched& S, const Epi& E) {
;     ...
;             const bool last = (t == nt - 2);
;             const char* a1 = cA + (size_t)(t + 1) * kstep;
;             const char* a2 = last ? nA : cA + (size_t)(t + 2) * kstep; const char* b2 = last ? nB : cB + (size_t)(t + 2) * kstep;
;             const char* a3 = a2 + kstep; const char* b3 = b2 + kstep;
;             if (last && has_next) S.a_ready(nxt);
;             if constexpr (SP2) {
;             PG8_LDB(B0, 0, 0); PG8_LDB(B1, 0, 1); PG8_SCHED; PG8_LDA(At, 0, 0); PG8_STAGE(PG8_SA(1, 1), a1 + hstep, voffA);
;             PG8_WAIT_V(8); PG8_WAIT_L(0); PG8_BAR; PG8_MMA(0, 0, At, B0); PG8_MMA(0, 1, At, B1); PG8_BAR; PG8_SCHED;
;             PG8_LDA(At, 0, 1); PG8_STAGE(PG8_SB(0, 0), b2, voffB); PG8_STAGE(PG8_SB(0, 1), b2 + hstep, voffB); PG8_STAGE(PG8_SA(0, 0), a2, voffA);
.LBB0_292:
	ds_read_b128 v[146:149], v164
	ds_read_b128 v[150:153], v164 offset:1024
	s_waitcnt lgkmcnt(0)
	ds_read_b128 v[154:157], v164 offset:2048
	ds_read_b128 v[168:171], v164 offset:3072
	ds_read_b128 v[172:175], v165
	ds_read_b128 v[176:179], v165 offset:1024
	ds_read_b128 v[180:183], v165 offset:2048
	ds_read_b128 v[184:187], v165 offset:3072
	s_add_u32 s40, s38, 0xfff00080
	s_addc_u32 s41, s39, -1
	s_cmp_eq_u32 s71, 60
	s_cselect_b32 s43, s33, s41
	s_cselect_b32 s42, s53, s40
	s_cselect_b32 s41, s51, s69
	s_cselect_b32 s40, s61, s68
	v_lshl_add_u64 v[222:223], s[38:39], 0, v[142:143]
	s_add_i32 m0, s19, 0xc000
	ds_read_b128 v[188:191], v166
	ds_read_b128 v[192:195], v166 offset:1024
	ds_read_b128 v[196:199], v166 offset:2048
	ds_read_b128 v[200:203], v166 offset:3072
	ds_read_b128 v[204:207], v166 offset:4096
	ds_read_b128 v[208:211], v166 offset:5120
	ds_read_b128 v[212:215], v166 offset:6144
	ds_read_b128 v[218:221], v166 offset:7168
	global_load_lds_dwordx4 v[222:223], off
	v_lshl_add_u64 v[222:223], s[38:39], 0, v[144:145]
	s_add_i32 m0, s19, 0xe000
	s_nop 0
	global_load_lds_dwordx4 v[222:223], off
	s_waitcnt vmcnt(8)
	s_waitcnt lgkmcnt(0)
	s_barrier
	s_setprio 1
	s_waitcnt lgkmcnt(0)
	v_mfma_f32_16x16x32_bf16 v[126:129], v[146:149], v[188:191], v[126:129]
	v_mfma_f32_16x16x32_bf16 v[122:125], v[154:157], v[188:191], v[122:125]
	v_mfma_f32_16x16x32_bf16 v[118:121], v[146:149], v[196:199], v[118:121]
	v_mfma_f32_16x16x32_bf16 v[110:113], v[154:157], v[196:199], v[110:113]
	v_mfma_f32_16x16x32_bf16 v[102:105], v[146:149], v[204:207], v[102:105]
	v_mfma_f32_16x16x32_bf16 v[94:97], v[154:157], v[204:207], v[94:97]
	v_mfma_f32_16x16x32_bf16 v[86:89], v[146:149], v[212:215], v[86:89]
	v_mfma_f32_16x16x32_bf16 v[78:81], v[154:157], v[212:215], v[78:81]
	v_mfma_f32_16x16x32_bf16 v[126:129], v[150:153], v[192:195], v[126:129]
	v_mfma_f32_16x16x32_bf16 v[122:125], v[168:171], v[192:195], v[122:125]
	v_mfma_f32_16x16x32_bf16 v[118:121], v[150:153], v[200:203], v[118:121]
	v_mfma_f32_16x16x32_bf16 v[110:113], v[168:171], v[200:203], v[110:113]
	v_mfma_f32_16x16x32_bf16 v[102:105], v[150:153], v[208:211], v[102:105]
	v_mfma_f32_16x16x32_bf16 v[94:97], v[168:171], v[208:211], v[94:97]
	v_mfma_f32_16x16x32_bf16 v[86:89], v[150:153], v[218:221], v[86:89]
	v_mfma_f32_16x16x32_bf16 v[78:81], v[168:171], v[218:221], v[78:81]
	v_mfma_f32_16x16x32_bf16 v[114:117], v[172:175], v[188:191], v[114:117]
	v_mfma_f32_16x16x32_bf16 v[106:109], v[180:183], v[188:191], v[106:109]
	v_mfma_f32_16x16x32_bf16 v[98:101], v[172:175], v[196:199], v[98:101]
	v_mfma_f32_16x16x32_bf16 v[90:93], v[180:183], v[196:199], v[90:93]
	v_mfma_f32_16x16x32_bf16 v[82:85], v[172:175], v[204:207], v[82:85]
	v_mfma_f32_16x16x32_bf16 v[74:77], v[180:183], v[204:207], v[74:77]
	v_mfma_f32_16x16x32_bf16 v[70:73], v[172:175], v[212:215], v[70:73]
	v_mfma_f32_16x16x32_bf16 v[66:69], v[180:183], v[212:215], v[66:69]
	v_mfma_f32_16x16x32_bf16 v[114:117], v[176:179], v[192:195], v[114:117]
	v_mfma_f32_16x16x32_bf16 v[106:109], v[184:187], v[192:195], v[106:109]
	v_mfma_f32_16x16x32_bf16 v[98:101], v[176:179], v[200:203], v[98:101]
	v_mfma_f32_16x16x32_bf16 v[90:93], v[184:187], v[200:203], v[90:93]
	v_mfma_f32_16x16x32_bf16 v[82:85], v[176:179], v[208:211], v[82:85]
	v_mfma_f32_16x16x32_bf16 v[74:77], v[184:187], v[208:211], v[74:77]
	v_mfma_f32_16x16x32_bf16 v[70:73], v[176:179], v[218:221], v[70:73]
	v_mfma_f32_16x16x32_bf16 v[66:69], v[184:187], v[218:221], v[66:69]
	s_setprio 0
	s_barrier
	s_add_i32 s72, s45, s17
	v_lshl_add_u64 v[222:223], s[40:41], 0, v[132:133]
	s_mov_b32 m0, s72
	ds_read_b128 v[188:191], v166 offset:16384
	ds_read_b128 v[192:195], v166 offset:17408
	ds_read_b128 v[196:199], v166 offset:18432
	ds_read_b128 v[200:203], v166 offset:19456
	ds_read_b128 v[204:207], v166 offset:20480
	ds_read_b128 v[208:211], v166 offset:21504
	ds_read_b128 v[212:215], v166 offset:22528
	ds_read_b128 v[218:221], v166 offset:23552
	global_load_lds_dwordx4 v[222:223], off
	s_add_i32 m0, s72, 0x2000
	s_add_u32 s72, s40, 0x100000
	v_lshl_add_u64 v[224:225], s[40:41], 0, v[136:137]
	s_addc_u32 s73, s41, 0
	s_add_i32 s74, s55, s17
	global_load_lds_dwordx4 v[224:225], off
	v_lshl_add_u64 v[226:227], s[72:73], 0, v[132:133]
	s_mov_b32 m0, s74
	v_lshl_add_u64 v[228:229], s[42:43], 0, v[134:135]
	global_load_lds_dwordx4 v[226:227], off
	v_lshl_add_u64 v[226:227], s[72:73], 0, v[136:137]
	s_add_i32 m0, s74, 0x2000
	s_nop 0
	global_load_lds_dwordx4 v[226:227], off
	v_lshl_add_u64 v[226:227], s[42:43], 0, v[130:131]
	s_mov_b32 m0, s19
	s_nop 0
	global_load_lds_dwordx4 v[226:227], off
	s_mov_b32 m0, s21
	s_nop 0
	global_load_lds_dwordx4 v[228:229], off
	s_waitcnt vmcnt(8)
	s_waitcnt lgkmcnt(0)
	s_barrier
; #define PG8_STAGE(bufoff, gbase, voff) do { _Pragma("unroll") for (int _i = 0; _i < 2; ++_i) \
;         __builtin_amdgcn_global_load_lds((const unsigned*)((const char*)(gbase) + (voff)[_i]), (PG8_LAS unsigned*)(lds + (bufoff) + ldsw + _i * 8192), 16, 0, 0); } while (0)
; #define PG8_LDA(dst, b, h) do { _Pragma("unroll") for (int m = 0; m < 4; ++m) _Pragma("unroll") for (int k = 0; k < 2; ++k) dst[m][k] = *(const PG8_LAS bf16x8*)(lds + PG8_SA(b, h) + aoff + m * 2048 + k * 1024); } while (0)
; #define PG8_LDB(dst, b, h) do { _Pragma("unroll") for (int n = 0; n < 2; ++n) _Pragma("unroll") for (int k = 0; k < 2; ++k) dst[n][k] = *(const PG8_LAS bf16x8*)(lds + PG8_SB(b, h) + boff + n * 2048 + k * 1024); } while (0)
; #define PG8_MMA(ai, bj, At, Bt) do { __builtin_amdgcn_s_setprio(1); _Pragma("unroll") for (int m = 0; m < 4; ++m) _Pragma("unroll") for (int n = 0; n < 2; ++n) _Pragma("unroll") for (int k = 0; k < 2; ++k) \
;         acc[ai][bj][m][n] = __builtin_amdgcn_mfma_f32_16x16x32_bf16(Bt[n][k], At[m][k], acc[ai][bj][m][n], 0, 0, 0); __builtin_amdgcn_s_setprio(0); } while (0)
; #define PG8_WAIT_V(n) asm volatile("s_waitcnt vmcnt(" #n ")" ::: "memory")
; #define PG8_WAIT_L(n) asm volatile("s_waitcnt lgkmcnt(" #n ")" ::: "memory")
; #define PG8_BAR __builtin_amdgcn_s_barrier()
; #define PG8_SCHED __builtin_amdgcn_sched_barrier(0)
; template <class Epi, class Sched, bool ALIGN_EPI = false, bool SP2 = false>
; __device__ __forceinline__ void gemm_phase(PG8_LAS unsigned char* lds, const Gemm g, const Sched& S, const Epi& E) {
;     ...
;             PG8_WAIT_V(8); PG8_WAIT_L(0); PG8_BAR; PG8_MMA(1, 0, At, B0); PG8_MMA(1, 1, At, B1); PG8_BAR; PG8_SCHED;
;             PG8_LDB(B0, 1, 0); PG8_LDB(B1, 1, 1); PG8_SCHED; PG8_LDA(At, 1, 0); PG8_STAGE(PG8_SA(0, 1), a2 + hstep, voffA);
;             PG8_WAIT_V(8); PG8_WAIT_L(0); PG8_BAR; PG8_MMA(0, 0, At, B0); PG8_MMA(0, 1, At, B1); PG8_BAR; PG8_SCHED;
	s_setprio 1
	s_waitcnt lgkmcnt(0)
	v_mfma_f32_16x16x32_bf16 v[62:65], v[146:149], v[188:191], v[62:65]
	v_mfma_f32_16x16x32_bf16 v[58:61], v[154:157], v[188:191], v[58:61]
	v_mfma_f32_16x16x32_bf16 v[54:57], v[146:149], v[196:199], v[54:57]
	v_mfma_f32_16x16x32_bf16 v[46:49], v[154:157], v[196:199], v[46:49]
	v_mfma_f32_16x16x32_bf16 v[38:41], v[146:149], v[204:207], v[38:41]
	v_mfma_f32_16x16x32_bf16 v[30:33], v[154:157], v[204:207], v[30:33]
	v_mfma_f32_16x16x32_bf16 v[22:25], v[146:149], v[212:215], v[22:25]
	v_mfma_f32_16x16x32_bf16 v[14:17], v[154:157], v[212:215], v[14:17]
	v_mfma_f32_16x16x32_bf16 v[62:65], v[150:153], v[192:195], v[62:65]
	v_mfma_f32_16x16x32_bf16 v[58:61], v[168:171], v[192:195], v[58:61]
	v_mfma_f32_16x16x32_bf16 v[54:57], v[150:153], v[200:203], v[54:57]
	v_mfma_f32_16x16x32_bf16 v[46:49], v[168:171], v[200:203], v[46:49]
	v_mfma_f32_16x16x32_bf16 v[38:41], v[150:153], v[208:211], v[38:41]
	v_mfma_f32_16x16x32_bf16 v[30:33], v[168:171], v[208:211], v[30:33]
	v_mfma_f32_16x16x32_bf16 v[22:25], v[150:153], v[218:221], v[22:25]
	v_mfma_f32_16x16x32_bf16 v[14:17], v[168:171], v[218:221], v[14:17]
	v_mfma_f32_16x16x32_bf16 v[50:53], v[172:175], v[188:191], v[50:53]
	v_mfma_f32_16x16x32_bf16 v[42:45], v[180:183], v[188:191], v[42:45]
	v_mfma_f32_16x16x32_bf16 v[34:37], v[172:175], v[196:199], v[34:37]
	v_mfma_f32_16x16x32_bf16 v[26:29], v[180:183], v[196:199], v[26:29]
	v_mfma_f32_16x16x32_bf16 v[18:21], v[172:175], v[204:207], v[18:21]
	v_mfma_f32_16x16x32_bf16 v[10:13], v[180:183], v[204:207], v[10:13]
	v_mfma_f32_16x16x32_bf16 v[6:9], v[172:175], v[212:215], v[6:9]
	v_mfma_f32_16x16x32_bf16 v[2:5], v[180:183], v[212:215], v[2:5]
	v_mfma_f32_16x16x32_bf16 v[50:53], v[176:179], v[192:195], v[50:53]
	v_mfma_f32_16x16x32_bf16 v[42:45], v[184:187], v[192:195], v[42:45]
	v_mfma_f32_16x16x32_bf16 v[34:37], v[176:179], v[200:203], v[34:37]
	v_mfma_f32_16x16x32_bf16 v[26:29], v[184:187], v[200:203], v[26:29]
	v_mfma_f32_16x16x32_bf16 v[18:21], v[176:179], v[208:211], v[18:21]
	v_mfma_f32_16x16x32_bf16 v[10:13], v[184:187], v[208:211], v[10:13]
	v_mfma_f32_16x16x32_bf16 v[6:9], v[176:179], v[218:221], v[6:9]
	v_mfma_f32_16x16x32_bf16 v[2:5], v[184:187], v[218:221], v[2:5]
	s_setprio 0
	s_barrier
	s_add_i32 s72, 0, 0x18000
	v_add_u32_e32 v139, s72, v158
	s_add_i32 s73, 0, 0x1c000
	ds_read_b128 v[146:149], v139
	ds_read_b128 v[150:153], v139 offset:1024
	ds_read_b128 v[154:157], v139 offset:2048
	ds_read_b128 v[168:171], v139 offset:3072
	v_add_u32_e32 v139, s73, v158
	ds_read_b128 v[172:175], v139
	ds_read_b128 v[176:179], v139 offset:1024
	ds_read_b128 v[180:183], v139 offset:2048
	ds_read_b128 v[184:187], v139 offset:3072
	s_add_u32 s42, s42, 0x100000
	s_addc_u32 s43, s43, 0
	s_mov_b32 m0, s23
	v_lshl_add_u64 v[230:231], s[42:43], 0, v[130:131]
	ds_read_b128 v[188:191], v166 offset:32768
	ds_read_b128 v[192:195], v166 offset:33792
	ds_read_b128 v[196:199], v166 offset:34816
	ds_read_b128 v[200:203], v166 offset:35840
	ds_read_b128 v[204:207], v166 offset:36864
	ds_read_b128 v[208:211], v166 offset:37888
	ds_read_b128 v[212:215], v166 offset:38912
	ds_read_b128 v[218:221], v166 offset:39936
	global_load_lds_dwordx4 v[230:231], off
	v_lshl_add_u64 v[230:231], s[42:43], 0, v[134:135]
	s_mov_b32 m0, s25
	s_nop 0
	global_load_lds_dwordx4 v[230:231], off
	s_waitcnt vmcnt(8)
	s_waitcnt lgkmcnt(0)
	s_barrier
	s_setprio 1
	s_waitcnt lgkmcnt(0)
	v_mfma_f32_16x16x32_bf16 v[126:129], v[146:149], v[188:191], v[126:129]
	v_mfma_f32_16x16x32_bf16 v[122:125], v[154:157], v[188:191], v[122:125]
	v_mfma_f32_16x16x32_bf16 v[118:121], v[146:149], v[196:199], v[118:121]
	v_mfma_f32_16x16x32_bf16 v[110:113], v[154:157], v[196:199], v[110:113]
	v_mfma_f32_16x16x32_bf16 v[102:105], v[146:149], v[204:207], v[102:105]
	v_mfma_f32_16x16x32_bf16 v[94:97], v[154:157], v[204:207], v[94:97]
	v_mfma_f32_16x16x32_bf16 v[86:89], v[146:149], v[212:215], v[86:89]
	v_mfma_f32_16x16x32_bf16 v[78:81], v[154:157], v[212:215], v[78:81]
	v_mfma_f32_16x16x32_bf16 v[126:129], v[150:153], v[192:195], v[126:129]
	v_mfma_f32_16x16x32_bf16 v[122:125], v[168:171], v[192:195], v[122:125]
	v_mfma_f32_16x16x32_bf16 v[118:121], v[150:153], v[200:203], v[118:121]
	v_mfma_f32_16x16x32_bf16 v[110:113], v[168:171], v[200:203], v[110:113]
	v_mfma_f32_16x16x32_bf16 v[102:105], v[150:153], v[208:211], v[102:105]
	v_mfma_f32_16x16x32_bf16 v[94:97], v[168:171], v[208:211], v[94:97]
	v_mfma_f32_16x16x32_bf16 v[86:89], v[150:153], v[218:221], v[86:89]
	v_mfma_f32_16x16x32_bf16 v[78:81], v[168:171], v[218:221], v[78:81]
	v_mfma_f32_16x16x32_bf16 v[114:117], v[172:175], v[188:191], v[114:117]
	v_mfma_f32_16x16x32_bf16 v[106:109], v[180:183], v[188:191], v[106:109]
	v_mfma_f32_16x16x32_bf16 v[98:101], v[172:175], v[196:199], v[98:101]
	v_mfma_f32_16x16x32_bf16 v[90:93], v[180:183], v[196:199], v[90:93]
	v_mfma_f32_16x16x32_bf16 v[82:85], v[172:175], v[204:207], v[82:85]
	v_mfma_f32_16x16x32_bf16 v[74:77], v[180:183], v[204:207], v[74:77]
	v_mfma_f32_16x16x32_bf16 v[70:73], v[172:175], v[212:215], v[70:73]
	v_mfma_f32_16x16x32_bf16 v[66:69], v[180:183], v[212:215], v[66:69]
	v_mfma_f32_16x16x32_bf16 v[114:117], v[176:179], v[192:195], v[114:117]
	v_mfma_f32_16x16x32_bf16 v[106:109], v[184:187], v[192:195], v[106:109]
	v_mfma_f32_16x16x32_bf16 v[98:101], v[176:179], v[200:203], v[98:101]
	v_mfma_f32_16x16x32_bf16 v[90:93], v[184:187], v[200:203], v[90:93]
	v_mfma_f32_16x16x32_bf16 v[82:85], v[176:179], v[208:211], v[82:85]
	v_mfma_f32_16x16x32_bf16 v[74:77], v[184:187], v[208:211], v[74:77]
	v_mfma_f32_16x16x32_bf16 v[70:73], v[176:179], v[218:221], v[70:73]
	v_mfma_f32_16x16x32_bf16 v[66:69], v[184:187], v[218:221], v[66:69]
	s_setprio 0
	s_barrier
; #define PG8_STAGE(bufoff, gbase, voff) do { _Pragma("unroll") for (int _i = 0; _i < 2; ++_i) \
;         __builtin_amdgcn_global_load_lds((const unsigned*)((const char*)(gbase) + (voff)[_i]), (PG8_LAS unsigned*)(lds + (bufoff) + ldsw + _i * 8192), 16, 0, 0); } while (0)
; #define PG8_LDA(dst, b, h) do { _Pragma("unroll") for (int m = 0; m < 4; ++m) _Pragma("unroll") for (int k = 0; k < 2; ++k) dst[m][k] = *(const PG8_LAS bf16x8*)(lds + PG8_SA(b, h) + aoff + m * 2048 + k * 1024); } while (0)
; #define PG8_MMA(ai, bj, At, Bt) do { __builtin_amdgcn_s_setprio(1); _Pragma("unroll") for (int m = 0; m < 4; ++m) _Pragma("unroll") for (int n = 0; n < 2; ++n) _Pragma("unroll") for (int k = 0; k < 2; ++k) \
;         acc[ai][bj][m][n] = __builtin_amdgcn_mfma_f32_16x16x32_bf16(Bt[n][k], At[m][k], acc[ai][bj][m][n], 0, 0, 0); __builtin_amdgcn_s_setprio(0); } while (0)
; #define PG8_WAIT_V(n) asm volatile("s_waitcnt vmcnt(" #n ")" ::: "memory")
; #define PG8_WAIT_L(n) asm volatile("s_waitcnt lgkmcnt(" #n ")" ::: "memory")
; #define PG8_BAR __builtin_amdgcn_s_barrier()
; #define PG8_SCHED __builtin_amdgcn_sched_barrier(0)
; template <class Epi, class Sched, bool ALIGN_EPI = false, bool SP2 = false>
; __device__ __forceinline__ void gemm_phase(PG8_LAS unsigned char* lds, const Gemm g, const Sched& S, const Epi& E) {
;     ...
;             PG8_LDA(At, 1, 1); PG8_STAGE(PG8_SB(1, 0), b3, voffB); PG8_STAGE(PG8_SB(1, 1), b3 + hstep, voffB); PG8_STAGE(PG8_SA(1, 0), a3, voffA);
;             PG8_WAIT_V(8); PG8_WAIT_L(0); PG8_BAR; PG8_MMA(1, 0, At, B0); PG8_MMA(1, 1, At, B1); PG8_BAR; PG8_SCHED;
;     ...
;         if constexpr (ALIGN_EPI) { if (wr == 0) PG8_BAR; }
;         if constexpr (!Epi::AFTER_DRAIN) { E(acc, cur, wr, wc, fr, fq); S.done(cur); }
;         if (!has_next) break;
	s_add_i32 s42, s72, s17
	v_lshl_add_u64 v[222:223], v[222:223], 0, s[10:11]
	s_mov_b32 m0, s42
	ds_read_b128 v[188:191], v166 offset:49152
	ds_read_b128 v[192:195], v166 offset:50176
	ds_read_b128 v[196:199], v166 offset:51200
	ds_read_b128 v[200:203], v166 offset:52224
	ds_read_b128 v[204:207], v166 offset:53248
	ds_read_b128 v[208:211], v166 offset:54272
	ds_read_b128 v[212:215], v166 offset:55296
	ds_read_b128 v[218:221], v166 offset:56320
	global_load_lds_dwordx4 v[222:223], off
	s_add_i32 m0, s42, 0x2000
	s_add_u32 s40, s40, 0x100080
	v_lshl_add_u64 v[222:223], v[224:225], 0, s[10:11]
	s_addc_u32 s41, s41, 0
	s_add_i32 s42, s73, s17
	global_load_lds_dwordx4 v[222:223], off
	v_lshl_add_u64 v[222:223], s[40:41], 0, v[132:133]
	s_mov_b32 m0, s42
	s_nop 0
	global_load_lds_dwordx4 v[222:223], off
	v_lshl_add_u64 v[222:223], s[40:41], 0, v[136:137]
	s_add_i32 m0, s42, 0x2000
	s_nop 0
	global_load_lds_dwordx4 v[222:223], off
	v_lshl_add_u64 v[222:223], v[226:227], 0, s[10:11]
	s_mov_b32 m0, s27
	s_nop 0
	global_load_lds_dwordx4 v[222:223], off
	v_lshl_add_u64 v[222:223], v[228:229], 0, s[10:11]
	s_mov_b32 m0, s29
	s_nop 0
	global_load_lds_dwordx4 v[222:223], off
	s_waitcnt vmcnt(8)
	s_waitcnt lgkmcnt(0)
	s_barrier
	s_setprio 1
	s_waitcnt lgkmcnt(0)
	v_mfma_f32_16x16x32_bf16 v[62:65], v[146:149], v[188:191], v[62:65]
	v_mfma_f32_16x16x32_bf16 v[58:61], v[154:157], v[188:191], v[58:61]
	v_mfma_f32_16x16x32_bf16 v[54:57], v[146:149], v[196:199], v[54:57]
	v_mfma_f32_16x16x32_bf16 v[46:49], v[154:157], v[196:199], v[46:49]
	v_mfma_f32_16x16x32_bf16 v[38:41], v[146:149], v[204:207], v[38:41]
	v_mfma_f32_16x16x32_bf16 v[30:33], v[154:157], v[204:207], v[30:33]
	v_mfma_f32_16x16x32_bf16 v[22:25], v[146:149], v[212:215], v[22:25]
	v_mfma_f32_16x16x32_bf16 v[14:17], v[154:157], v[212:215], v[14:17]
	v_mfma_f32_16x16x32_bf16 v[62:65], v[150:153], v[192:195], v[62:65]
	v_mfma_f32_16x16x32_bf16 v[58:61], v[168:171], v[192:195], v[58:61]
	v_mfma_f32_16x16x32_bf16 v[54:57], v[150:153], v[200:203], v[54:57]
	v_mfma_f32_16x16x32_bf16 v[46:49], v[168:171], v[200:203], v[46:49]
	v_mfma_f32_16x16x32_bf16 v[38:41], v[150:153], v[208:211], v[38:41]
	v_mfma_f32_16x16x32_bf16 v[30:33], v[168:171], v[208:211], v[30:33]
	v_mfma_f32_16x16x32_bf16 v[22:25], v[150:153], v[218:221], v[22:25]
	v_mfma_f32_16x16x32_bf16 v[14:17], v[168:171], v[218:221], v[14:17]
	v_mfma_f32_16x16x32_bf16 v[50:53], v[172:175], v[188:191], v[50:53]
	v_mfma_f32_16x16x32_bf16 v[42:45], v[180:183], v[188:191], v[42:45]
	v_mfma_f32_16x16x32_bf16 v[34:37], v[172:175], v[196:199], v[34:37]
	v_mfma_f32_16x16x32_bf16 v[26:29], v[180:183], v[196:199], v[26:29]
	v_mfma_f32_16x16x32_bf16 v[18:21], v[172:175], v[204:207], v[18:21]
	v_mfma_f32_16x16x32_bf16 v[10:13], v[180:183], v[204:207], v[10:13]
	v_mfma_f32_16x16x32_bf16 v[6:9], v[172:175], v[212:215], v[6:9]
	v_mfma_f32_16x16x32_bf16 v[2:5], v[180:183], v[212:215], v[2:5]
	v_mfma_f32_16x16x32_bf16 v[50:53], v[176:179], v[192:195], v[50:53]
	v_mfma_f32_16x16x32_bf16 v[42:45], v[184:187], v[192:195], v[42:45]
	v_mfma_f32_16x16x32_bf16 v[34:37], v[176:179], v[200:203], v[34:37]
	v_mfma_f32_16x16x32_bf16 v[26:29], v[184:187], v[200:203], v[26:29]
	v_mfma_f32_16x16x32_bf16 v[18:21], v[176:179], v[208:211], v[18:21]
	v_mfma_f32_16x16x32_bf16 v[10:13], v[184:187], v[208:211], v[10:13]
	v_mfma_f32_16x16x32_bf16 v[6:9], v[176:179], v[218:221], v[6:9]
	v_mfma_f32_16x16x32_bf16 v[2:5], v[184:187], v[218:221], v[2:5]
	s_setprio 0
	s_barrier
	s_add_i32 s71, s71, 2
	s_add_u32 s38, s38, 0x100
	s_addc_u32 s39, s39, 0
	s_add_u32 s68, s68, 0x100
	s_addc_u32 s69, s69, 0
	s_cmp_gt_u32 s71, 61
	s_cbranch_scc0 .LBB0_292
	s_and_b64 vcc, exec, s[12:13]
	s_cbranch_vccnz .LBB0_300
	v_lshl_add_u32 v146, s0, 8, v1
	s_cmp_gt_u32 s54, 7
	s_mov_b64 s[38:39], -1
	s_cbranch_scc1 .LBB0_301

; #define PG8_STAGE(bufoff, gbase, voff) do { _Pragma("unroll") for (int _i = 0; _i < 2; ++_i) \
;         __builtin_amdgcn_global_load_lds((const unsigned*)((const char*)(gbase) + (voff)[_i]), (PG8_LAS unsigned*)(lds + (bufoff) + ldsw + _i * 8192), 16, 0, 0); } while (0)
; #define PG8_LDA(dst, b, h) do { _Pragma("unroll") for (int m = 0; m < 4; ++m) _Pragma("unroll") for (int k = 0; k < 2; ++k) dst[m][k] = *(const PG8_LAS bf16x8*)(lds + PG8_SA(b, h) + aoff + m * 2048 + k * 1024); } while (0)
; #define PG8_LDB(dst, b, h) do { _Pragma("unroll") for (int n = 0; n < 2; ++n) _Pragma("unroll") for (int k = 0; k < 2; ++k) dst[n][k] = *(const PG8_LAS bf16x8*)(lds + PG8_SB(b, h) + boff + n * 2048 + k * 1024); } while (0)
; #define PG8_MMA(ai, bj, At, Bt) do { __builtin_amdgcn_s_setprio(1); _Pragma("unroll") for (int m = 0; m < 4; ++m) _Pragma("unroll") for (int n = 0; n < 2; ++n) _Pragma("unroll") for (int k = 0; k < 2; ++k) \
;         acc[ai][bj][m][n] = __builtin_amdgcn_mfma_f32_16x16x32_bf16(Bt[n][k], At[m][k], acc[ai][bj][m][n], 0, 0, 0); __builtin_amdgcn_s_setprio(0); } while (0)
; #define PG8_WAIT_V(n) asm volatile("s_waitcnt vmcnt(" #n ")" ::: "memory")
; #define PG8_WAIT_L(n) asm volatile("s_waitcnt lgkmcnt(" #n ")" ::: "memory")
; #define PG8_BAR __builtin_amdgcn_s_barrier()
; #define PG8_SCHED __builtin_amdgcn_sched_barrier(0)
; template <class Epi, class Sched, bool ALIGN_EPI = false, bool SP2 = false>
; __device__ __forceinline__ void gemm_phase(PG8_LAS unsigned char* lds, const Gemm g, const Sched& S, const Epi& E) {
;     ...
;             const bool last = (t == nt - 2);
;             const char* a1 = cA + (size_t)(t + 1) * kstep;
;             const char* a2 = last ? nA : cA + (size_t)(t + 2) * kstep; const char* b2 = last ? nB : cB + (size_t)(t + 2) * kstep;
;             const char* a3 = a2 + kstep; const char* b3 = b2 + kstep;
;             if (last && has_next) S.a_ready(nxt);
;             if constexpr (SP2) {
;             PG8_LDB(B0, 0, 0); PG8_LDB(B1, 0, 1); PG8_SCHED; PG8_LDA(At, 0, 0); PG8_STAGE(PG8_SA(1, 1), a1 + hstep, voffA);
;             PG8_WAIT_V(8); PG8_WAIT_L(0); PG8_BAR; PG8_MMA(0, 0, At, B0); PG8_MMA(0, 1, At, B1); PG8_BAR; PG8_SCHED;
;             PG8_LDA(At, 0, 1); PG8_STAGE(PG8_SB(0, 0), b2, voffB); PG8_STAGE(PG8_SB(0, 1), b2 + hstep, voffB); PG8_STAGE(PG8_SA(0, 0), a2, voffA);
.LBB0_781:
	ds_read_b128 v[146:149], v152
	ds_read_b128 v[156:159], v152 offset:1024
	ds_read_b128 v[160:163], v152 offset:2048
	ds_read_b128 v[164:167], v152 offset:3072
	ds_read_b128 v[168:171], v153
	ds_read_b128 v[172:175], v153 offset:1024
	ds_read_b128 v[176:179], v153 offset:2048
	ds_read_b128 v[180:183], v153 offset:3072
	s_add_u32 s38, s36, 0xfff00080
	s_addc_u32 s39, s37, -1
	s_cmp_eq_u32 s56, 60
	s_cselect_b32 s41, s25, s39
	s_cselect_b32 s40, s31, s38
	s_cselect_b32 s39, s23, s55
	s_cselect_b32 s38, s35, s54
	v_lshl_add_u64 v[218:219], s[36:37], 0, v[138:139]
	s_add_i32 m0, s44, 0xc000
	ds_read_b128 v[184:187], v154
	ds_read_b128 v[188:191], v154 offset:1024
	ds_read_b128 v[192:195], v154 offset:2048
	ds_read_b128 v[196:199], v154 offset:3072
	ds_read_b128 v[200:203], v154 offset:4096
	ds_read_b128 v[204:207], v154 offset:5120
	ds_read_b128 v[208:211], v154 offset:6144
	ds_read_b128 v[212:215], v154 offset:7168
	global_load_lds_dwordx4 v[218:219], off
	v_lshl_add_u64 v[218:219], s[36:37], 0, v[140:141]
	s_add_i32 m0, s44, 0xe000
	s_nop 0
	global_load_lds_dwordx4 v[218:219], off
	s_waitcnt vmcnt(8)
	s_waitcnt lgkmcnt(0)
	s_barrier
	s_setprio 1
	s_waitcnt lgkmcnt(0)
	v_mfma_f32_16x16x32_bf16 v[126:129], v[146:149], v[184:187], v[126:129]
	v_mfma_f32_16x16x32_bf16 v[122:125], v[160:163], v[184:187], v[122:125]
	v_mfma_f32_16x16x32_bf16 v[110:113], v[146:149], v[192:195], v[110:113]
	v_mfma_f32_16x16x32_bf16 v[106:109], v[160:163], v[192:195], v[106:109]
	v_mfma_f32_16x16x32_bf16 v[94:97], v[146:149], v[200:203], v[94:97]
	v_mfma_f32_16x16x32_bf16 v[90:93], v[160:163], v[200:203], v[90:93]
	v_mfma_f32_16x16x32_bf16 v[78:81], v[146:149], v[208:211], v[78:81]
	v_mfma_f32_16x16x32_bf16 v[74:77], v[160:163], v[208:211], v[74:77]
	v_mfma_f32_16x16x32_bf16 v[126:129], v[156:159], v[188:191], v[126:129]
	v_mfma_f32_16x16x32_bf16 v[122:125], v[164:167], v[188:191], v[122:125]
	v_mfma_f32_16x16x32_bf16 v[110:113], v[156:159], v[196:199], v[110:113]
	v_mfma_f32_16x16x32_bf16 v[106:109], v[164:167], v[196:199], v[106:109]
	v_mfma_f32_16x16x32_bf16 v[94:97], v[156:159], v[204:207], v[94:97]
	v_mfma_f32_16x16x32_bf16 v[90:93], v[164:167], v[204:207], v[90:93]
	v_mfma_f32_16x16x32_bf16 v[78:81], v[156:159], v[212:215], v[78:81]
	v_mfma_f32_16x16x32_bf16 v[74:77], v[164:167], v[212:215], v[74:77]
	v_mfma_f32_16x16x32_bf16 v[118:121], v[168:171], v[184:187], v[118:121]
	v_mfma_f32_16x16x32_bf16 v[114:117], v[176:179], v[184:187], v[114:117]
	v_mfma_f32_16x16x32_bf16 v[102:105], v[168:171], v[192:195], v[102:105]
	v_mfma_f32_16x16x32_bf16 v[98:101], v[176:179], v[192:195], v[98:101]
	v_mfma_f32_16x16x32_bf16 v[86:89], v[168:171], v[200:203], v[86:89]
	v_mfma_f32_16x16x32_bf16 v[82:85], v[176:179], v[200:203], v[82:85]
	v_mfma_f32_16x16x32_bf16 v[70:73], v[168:171], v[208:211], v[70:73]
	v_mfma_f32_16x16x32_bf16 v[66:69], v[176:179], v[208:211], v[66:69]
	v_mfma_f32_16x16x32_bf16 v[118:121], v[172:175], v[188:191], v[118:121]
	v_mfma_f32_16x16x32_bf16 v[114:117], v[180:183], v[188:191], v[114:117]
	v_mfma_f32_16x16x32_bf16 v[102:105], v[172:175], v[196:199], v[102:105]
	v_mfma_f32_16x16x32_bf16 v[98:101], v[180:183], v[196:199], v[98:101]
	v_mfma_f32_16x16x32_bf16 v[86:89], v[172:175], v[204:207], v[86:89]
	v_mfma_f32_16x16x32_bf16 v[82:85], v[180:183], v[204:207], v[82:85]
	v_mfma_f32_16x16x32_bf16 v[70:73], v[172:175], v[212:215], v[70:73]
	v_mfma_f32_16x16x32_bf16 v[66:69], v[180:183], v[212:215], v[66:69]
	s_setprio 0
	s_barrier
	s_add_i32 s57, s52, s33
	v_lshl_add_u64 v[218:219], s[38:39], 0, v[132:133]
	s_mov_b32 m0, s57
	ds_read_b128 v[184:187], v154 offset:16384
	ds_read_b128 v[188:191], v154 offset:17408
	ds_read_b128 v[192:195], v154 offset:18432
	ds_read_b128 v[196:199], v154 offset:19456
	ds_read_b128 v[200:203], v154 offset:20480
	ds_read_b128 v[204:207], v154 offset:21504
	ds_read_b128 v[208:211], v154 offset:22528
	ds_read_b128 v[212:215], v154 offset:23552
	global_load_lds_dwordx4 v[218:219], off
	s_add_i32 m0, s57, 0x2000
	s_add_u32 s58, s38, 0x100000
	v_lshl_add_u64 v[220:221], s[38:39], 0, v[136:137]
	s_addc_u32 s59, s39, 0
	s_add_i32 s57, s53, s33
	global_load_lds_dwordx4 v[220:221], off
	v_lshl_add_u64 v[222:223], s[58:59], 0, v[132:133]
	s_mov_b32 m0, s57
	v_lshl_add_u64 v[224:225], s[40:41], 0, v[134:135]
	global_load_lds_dwordx4 v[222:223], off
	v_lshl_add_u64 v[222:223], s[58:59], 0, v[136:137]
	s_add_i32 m0, s57, 0x2000
	s_nop 0
	global_load_lds_dwordx4 v[222:223], off
	v_lshl_add_u64 v[222:223], s[40:41], 0, v[130:131]
	s_mov_b32 m0, s44
	s_nop 0
	global_load_lds_dwordx4 v[222:223], off
	s_mov_b32 m0, s45
	s_nop 0
	global_load_lds_dwordx4 v[224:225], off
	s_waitcnt vmcnt(8)
	s_waitcnt lgkmcnt(0)
	s_barrier
; #define PG8_STAGE(bufoff, gbase, voff) do { _Pragma("unroll") for (int _i = 0; _i < 2; ++_i) \
;         __builtin_amdgcn_global_load_lds((const unsigned*)((const char*)(gbase) + (voff)[_i]), (PG8_LAS unsigned*)(lds + (bufoff) + ldsw + _i * 8192), 16, 0, 0); } while (0)
; #define PG8_LDA(dst, b, h) do { _Pragma("unroll") for (int m = 0; m < 4; ++m) _Pragma("unroll") for (int k = 0; k < 2; ++k) dst[m][k] = *(const PG8_LAS bf16x8*)(lds + PG8_SA(b, h) + aoff + m * 2048 + k * 1024); } while (0)
; #define PG8_LDB(dst, b, h) do { _Pragma("unroll") for (int n = 0; n < 2; ++n) _Pragma("unroll") for (int k = 0; k < 2; ++k) dst[n][k] = *(const PG8_LAS bf16x8*)(lds + PG8_SB(b, h) + boff + n * 2048 + k * 1024); } while (0)
; #define PG8_MMA(ai, bj, At, Bt) do { __builtin_amdgcn_s_setprio(1); _Pragma("unroll") for (int m = 0; m < 4; ++m) _Pragma("unroll") for (int n = 0; n < 2; ++n) _Pragma("unroll") for (int k = 0; k < 2; ++k) \
;         acc[ai][bj][m][n] = __builtin_amdgcn_mfma_f32_16x16x32_bf16(Bt[n][k], At[m][k], acc[ai][bj][m][n], 0, 0, 0); __builtin_amdgcn_s_setprio(0); } while (0)
; #define PG8_WAIT_V(n) asm volatile("s_waitcnt vmcnt(" #n ")" ::: "memory")
; #define PG8_WAIT_L(n) asm volatile("s_waitcnt lgkmcnt(" #n ")" ::: "memory")
; #define PG8_BAR __builtin_amdgcn_s_barrier()
; #define PG8_SCHED __builtin_amdgcn_sched_barrier(0)
; template <class Epi, class Sched, bool ALIGN_EPI = false, bool SP2 = false>
; __device__ __forceinline__ void gemm_phase(PG8_LAS unsigned char* lds, const Gemm g, const Sched& S, const Epi& E) {
;     ...
;             PG8_WAIT_V(8); PG8_WAIT_L(0); PG8_BAR; PG8_MMA(1, 0, At, B0); PG8_MMA(1, 1, At, B1); PG8_BAR; PG8_SCHED;
;             PG8_LDB(B0, 1, 0); PG8_LDB(B1, 1, 1); PG8_SCHED; PG8_LDA(At, 1, 0); PG8_STAGE(PG8_SA(0, 1), a2 + hstep, voffA);
;             PG8_WAIT_V(8); PG8_WAIT_L(0); PG8_BAR; PG8_MMA(0, 0, At, B0); PG8_MMA(0, 1, At, B1); PG8_BAR; PG8_SCHED;
	s_setprio 1
	s_waitcnt lgkmcnt(0)
	v_mfma_f32_16x16x32_bf16 v[62:65], v[146:149], v[184:187], v[62:65]
	v_mfma_f32_16x16x32_bf16 v[58:61], v[160:163], v[184:187], v[58:61]
	v_mfma_f32_16x16x32_bf16 v[46:49], v[146:149], v[192:195], v[46:49]
	v_mfma_f32_16x16x32_bf16 v[42:45], v[160:163], v[192:195], v[42:45]
	v_mfma_f32_16x16x32_bf16 v[30:33], v[146:149], v[200:203], v[30:33]
	v_mfma_f32_16x16x32_bf16 v[26:29], v[160:163], v[200:203], v[26:29]
	v_mfma_f32_16x16x32_bf16 v[14:17], v[146:149], v[208:211], v[14:17]
	v_mfma_f32_16x16x32_bf16 v[10:13], v[160:163], v[208:211], v[10:13]
	v_mfma_f32_16x16x32_bf16 v[62:65], v[156:159], v[188:191], v[62:65]
	v_mfma_f32_16x16x32_bf16 v[58:61], v[164:167], v[188:191], v[58:61]
	v_mfma_f32_16x16x32_bf16 v[46:49], v[156:159], v[196:199], v[46:49]
	v_mfma_f32_16x16x32_bf16 v[42:45], v[164:167], v[196:199], v[42:45]
	v_mfma_f32_16x16x32_bf16 v[30:33], v[156:159], v[204:207], v[30:33]
	v_mfma_f32_16x16x32_bf16 v[26:29], v[164:167], v[204:207], v[26:29]
	v_mfma_f32_16x16x32_bf16 v[14:17], v[156:159], v[212:215], v[14:17]
	v_mfma_f32_16x16x32_bf16 v[10:13], v[164:167], v[212:215], v[10:13]
	v_mfma_f32_16x16x32_bf16 v[54:57], v[168:171], v[184:187], v[54:57]
	v_mfma_f32_16x16x32_bf16 v[50:53], v[176:179], v[184:187], v[50:53]
	v_mfma_f32_16x16x32_bf16 v[38:41], v[168:171], v[192:195], v[38:41]
	v_mfma_f32_16x16x32_bf16 v[34:37], v[176:179], v[192:195], v[34:37]
	v_mfma_f32_16x16x32_bf16 v[22:25], v[168:171], v[200:203], v[22:25]
	v_mfma_f32_16x16x32_bf16 v[18:21], v[176:179], v[200:203], v[18:21]
	v_mfma_f32_16x16x32_bf16 v[6:9], v[168:171], v[208:211], v[6:9]
	v_mfma_f32_16x16x32_bf16 v[2:5], v[176:179], v[208:211], v[2:5]
	v_mfma_f32_16x16x32_bf16 v[54:57], v[172:175], v[188:191], v[54:57]
	v_mfma_f32_16x16x32_bf16 v[50:53], v[180:183], v[188:191], v[50:53]
	v_mfma_f32_16x16x32_bf16 v[38:41], v[172:175], v[196:199], v[38:41]
	v_mfma_f32_16x16x32_bf16 v[34:37], v[180:183], v[196:199], v[34:37]
	v_mfma_f32_16x16x32_bf16 v[22:25], v[172:175], v[204:207], v[22:25]
	v_mfma_f32_16x16x32_bf16 v[18:21], v[180:183], v[204:207], v[18:21]
	v_mfma_f32_16x16x32_bf16 v[6:9], v[172:175], v[212:215], v[6:9]
	v_mfma_f32_16x16x32_bf16 v[2:5], v[180:183], v[212:215], v[2:5]
	s_setprio 0
	s_barrier
	s_add_i32 s57, 0, 0x18000
	s_add_i32 s58, 0, 0x1c000
	v_add_u32_e32 v164, s57, v150
	v_add_u32_e32 v180, s58, v150
	ds_read_b128 v[146:149], v164
	ds_read_b128 v[156:159], v164 offset:1024
	ds_read_b128 v[160:163], v164 offset:2048
	ds_read_b128 v[164:167], v164 offset:3072
	ds_read_b128 v[168:171], v180
	ds_read_b128 v[172:175], v180 offset:1024
	ds_read_b128 v[176:179], v180 offset:2048
	ds_read_b128 v[180:183], v180 offset:3072
	s_add_u32 s40, s40, 0x100000
	s_addc_u32 s41, s41, 0
	s_mov_b32 m0, s46
	v_lshl_add_u64 v[226:227], s[40:41], 0, v[130:131]
	ds_read_b128 v[184:187], v154 offset:32768
	ds_read_b128 v[188:191], v154 offset:33792
	ds_read_b128 v[192:195], v154 offset:34816
	ds_read_b128 v[196:199], v154 offset:35840
	ds_read_b128 v[200:203], v154 offset:36864
	ds_read_b128 v[204:207], v154 offset:37888
	ds_read_b128 v[208:211], v154 offset:38912
	ds_read_b128 v[212:215], v154 offset:39936
	global_load_lds_dwordx4 v[226:227], off
	v_lshl_add_u64 v[226:227], s[40:41], 0, v[134:135]
	s_mov_b32 m0, s47
	s_nop 0
	global_load_lds_dwordx4 v[226:227], off
	s_waitcnt vmcnt(8)
	s_waitcnt lgkmcnt(0)
	s_barrier
	s_setprio 1
	s_waitcnt lgkmcnt(0)
	v_mfma_f32_16x16x32_bf16 v[126:129], v[146:149], v[184:187], v[126:129]
	v_mfma_f32_16x16x32_bf16 v[122:125], v[160:163], v[184:187], v[122:125]
	v_mfma_f32_16x16x32_bf16 v[110:113], v[146:149], v[192:195], v[110:113]
	v_mfma_f32_16x16x32_bf16 v[106:109], v[160:163], v[192:195], v[106:109]
	v_mfma_f32_16x16x32_bf16 v[94:97], v[146:149], v[200:203], v[94:97]
	v_mfma_f32_16x16x32_bf16 v[90:93], v[160:163], v[200:203], v[90:93]
	v_mfma_f32_16x16x32_bf16 v[78:81], v[146:149], v[208:211], v[78:81]
	v_mfma_f32_16x16x32_bf16 v[74:77], v[160:163], v[208:211], v[74:77]
	v_mfma_f32_16x16x32_bf16 v[126:129], v[156:159], v[188:191], v[126:129]
	v_mfma_f32_16x16x32_bf16 v[122:125], v[164:167], v[188:191], v[122:125]
	v_mfma_f32_16x16x32_bf16 v[110:113], v[156:159], v[196:199], v[110:113]
	v_mfma_f32_16x16x32_bf16 v[106:109], v[164:167], v[196:199], v[106:109]
	v_mfma_f32_16x16x32_bf16 v[94:97], v[156:159], v[204:207], v[94:97]
	v_mfma_f32_16x16x32_bf16 v[90:93], v[164:167], v[204:207], v[90:93]
	v_mfma_f32_16x16x32_bf16 v[78:81], v[156:159], v[212:215], v[78:81]
	v_mfma_f32_16x16x32_bf16 v[74:77], v[164:167], v[212:215], v[74:77]
	v_mfma_f32_16x16x32_bf16 v[118:121], v[168:171], v[184:187], v[118:121]
	v_mfma_f32_16x16x32_bf16 v[114:117], v[176:179], v[184:187], v[114:117]
	v_mfma_f32_16x16x32_bf16 v[102:105], v[168:171], v[192:195], v[102:105]
	v_mfma_f32_16x16x32_bf16 v[98:101], v[176:179], v[192:195], v[98:101]
	v_mfma_f32_16x16x32_bf16 v[86:89], v[168:171], v[200:203], v[86:89]
	v_mfma_f32_16x16x32_bf16 v[82:85], v[176:179], v[200:203], v[82:85]
	v_mfma_f32_16x16x32_bf16 v[70:73], v[168:171], v[208:211], v[70:73]
	v_mfma_f32_16x16x32_bf16 v[66:69], v[176:179], v[208:211], v[66:69]
	v_mfma_f32_16x16x32_bf16 v[118:121], v[172:175], v[188:191], v[118:121]
	v_mfma_f32_16x16x32_bf16 v[114:117], v[180:183], v[188:191], v[114:117]
	v_mfma_f32_16x16x32_bf16 v[102:105], v[172:175], v[196:199], v[102:105]
	v_mfma_f32_16x16x32_bf16 v[98:101], v[180:183], v[196:199], v[98:101]
	v_mfma_f32_16x16x32_bf16 v[86:89], v[172:175], v[204:207], v[86:89]
	v_mfma_f32_16x16x32_bf16 v[82:85], v[180:183], v[204:207], v[82:85]
	v_mfma_f32_16x16x32_bf16 v[70:73], v[172:175], v[212:215], v[70:73]
	v_mfma_f32_16x16x32_bf16 v[66:69], v[180:183], v[212:215], v[66:69]
	s_setprio 0
	s_barrier
; #define PG8_STAGE(bufoff, gbase, voff) do { _Pragma("unroll") for (int _i = 0; _i < 2; ++_i) \
;         __builtin_amdgcn_global_load_lds((const unsigned*)((const char*)(gbase) + (voff)[_i]), (PG8_LAS unsigned*)(lds + (bufoff) + ldsw + _i * 8192), 16, 0, 0); } while (0)
; #define PG8_LDA(dst, b, h) do { _Pragma("unroll") for (int m = 0; m < 4; ++m) _Pragma("unroll") for (int k = 0; k < 2; ++k) dst[m][k] = *(const PG8_LAS bf16x8*)(lds + PG8_SA(b, h) + aoff + m * 2048 + k * 1024); } while (0)
; #define PG8_MMA(ai, bj, At, Bt) do { __builtin_amdgcn_s_setprio(1); _Pragma("unroll") for (int m = 0; m < 4; ++m) _Pragma("unroll") for (int n = 0; n < 2; ++n) _Pragma("unroll") for (int k = 0; k < 2; ++k) \
;         acc[ai][bj][m][n] = __builtin_amdgcn_mfma_f32_16x16x32_bf16(Bt[n][k], At[m][k], acc[ai][bj][m][n], 0, 0, 0); __builtin_amdgcn_s_setprio(0); } while (0)
; #define PG8_WAIT_V(n) asm volatile("s_waitcnt vmcnt(" #n ")" ::: "memory")
; #define PG8_WAIT_L(n) asm volatile("s_waitcnt lgkmcnt(" #n ")" ::: "memory")
; #define PG8_BAR __builtin_amdgcn_s_barrier()
; #define PG8_SCHED __builtin_amdgcn_sched_barrier(0)
; template <class Epi, class Sched, bool ALIGN_EPI = false, bool SP2 = false>
; __device__ __forceinline__ void gemm_phase(PG8_LAS unsigned char* lds, const Gemm g, const Sched& S, const Epi& E) {
;     ...
;             PG8_LDA(At, 1, 1); PG8_STAGE(PG8_SB(1, 0), b3, voffB); PG8_STAGE(PG8_SB(1, 1), b3 + hstep, voffB); PG8_STAGE(PG8_SA(1, 0), a3, voffA);
;             PG8_WAIT_V(8); PG8_WAIT_L(0); PG8_BAR; PG8_MMA(1, 0, At, B0); PG8_MMA(1, 1, At, B1); PG8_BAR; PG8_SCHED;
;     ...
;         }
;         if constexpr (ALIGN_EPI) { if (wr == 0) PG8_BAR; }
	s_add_i32 s40, s57, s33
	v_lshl_add_u64 v[218:219], v[218:219], 0, s[14:15]
	s_mov_b32 m0, s40
	ds_read_b128 v[184:187], v154 offset:49152
	ds_read_b128 v[188:191], v154 offset:50176
	ds_read_b128 v[192:195], v154 offset:51200
	ds_read_b128 v[196:199], v154 offset:52224
	ds_read_b128 v[200:203], v154 offset:53248
	ds_read_b128 v[204:207], v154 offset:54272
	ds_read_b128 v[208:211], v154 offset:55296
	ds_read_b128 v[212:215], v154 offset:56320
	global_load_lds_dwordx4 v[218:219], off
	s_add_i32 m0, s40, 0x2000
	s_add_u32 s38, s38, 0x100080
	v_lshl_add_u64 v[218:219], v[220:221], 0, s[14:15]
	s_addc_u32 s39, s39, 0
	s_add_i32 s40, s58, s33
	global_load_lds_dwordx4 v[218:219], off
	v_lshl_add_u64 v[218:219], s[38:39], 0, v[132:133]
	s_mov_b32 m0, s40
	s_nop 0
	global_load_lds_dwordx4 v[218:219], off
	v_lshl_add_u64 v[218:219], s[38:39], 0, v[136:137]
	s_add_i32 m0, s40, 0x2000
	s_nop 0
	global_load_lds_dwordx4 v[218:219], off
	v_lshl_add_u64 v[218:219], v[222:223], 0, s[14:15]
	s_mov_b32 m0, s50
	s_nop 0
	global_load_lds_dwordx4 v[218:219], off
	v_lshl_add_u64 v[218:219], v[224:225], 0, s[14:15]
	s_mov_b32 m0, s51
	s_nop 0
	global_load_lds_dwordx4 v[218:219], off
	s_waitcnt vmcnt(8)
	s_waitcnt lgkmcnt(0)
	s_barrier
	s_setprio 1
	s_waitcnt lgkmcnt(0)
	v_mfma_f32_16x16x32_bf16 v[62:65], v[146:149], v[184:187], v[62:65]
	v_mfma_f32_16x16x32_bf16 v[58:61], v[160:163], v[184:187], v[58:61]
	v_mfma_f32_16x16x32_bf16 v[46:49], v[146:149], v[192:195], v[46:49]
	v_mfma_f32_16x16x32_bf16 v[42:45], v[160:163], v[192:195], v[42:45]
	v_mfma_f32_16x16x32_bf16 v[30:33], v[146:149], v[200:203], v[30:33]
	v_mfma_f32_16x16x32_bf16 v[26:29], v[160:163], v[200:203], v[26:29]
	v_mfma_f32_16x16x32_bf16 v[14:17], v[146:149], v[208:211], v[14:17]
	v_mfma_f32_16x16x32_bf16 v[10:13], v[160:163], v[208:211], v[10:13]
	v_mfma_f32_16x16x32_bf16 v[62:65], v[156:159], v[188:191], v[62:65]
	v_mfma_f32_16x16x32_bf16 v[58:61], v[164:167], v[188:191], v[58:61]
	v_mfma_f32_16x16x32_bf16 v[46:49], v[156:159], v[196:199], v[46:49]
	v_mfma_f32_16x16x32_bf16 v[42:45], v[164:167], v[196:199], v[42:45]
	v_mfma_f32_16x16x32_bf16 v[30:33], v[156:159], v[204:207], v[30:33]
	v_mfma_f32_16x16x32_bf16 v[26:29], v[164:167], v[204:207], v[26:29]
	v_mfma_f32_16x16x32_bf16 v[14:17], v[156:159], v[212:215], v[14:17]
	v_mfma_f32_16x16x32_bf16 v[10:13], v[164:167], v[212:215], v[10:13]
	v_mfma_f32_16x16x32_bf16 v[54:57], v[168:171], v[184:187], v[54:57]
	v_mfma_f32_16x16x32_bf16 v[50:53], v[176:179], v[184:187], v[50:53]
	v_mfma_f32_16x16x32_bf16 v[38:41], v[168:171], v[192:195], v[38:41]
	v_mfma_f32_16x16x32_bf16 v[34:37], v[176:179], v[192:195], v[34:37]
	v_mfma_f32_16x16x32_bf16 v[22:25], v[168:171], v[200:203], v[22:25]
	v_mfma_f32_16x16x32_bf16 v[18:21], v[176:179], v[200:203], v[18:21]
	v_mfma_f32_16x16x32_bf16 v[6:9], v[168:171], v[208:211], v[6:9]
	v_mfma_f32_16x16x32_bf16 v[2:5], v[176:179], v[208:211], v[2:5]
	v_mfma_f32_16x16x32_bf16 v[54:57], v[172:175], v[188:191], v[54:57]
	v_mfma_f32_16x16x32_bf16 v[50:53], v[180:183], v[188:191], v[50:53]
	v_mfma_f32_16x16x32_bf16 v[38:41], v[172:175], v[196:199], v[38:41]
	v_mfma_f32_16x16x32_bf16 v[34:37], v[180:183], v[196:199], v[34:37]
	v_mfma_f32_16x16x32_bf16 v[22:25], v[172:175], v[204:207], v[22:25]
	v_mfma_f32_16x16x32_bf16 v[18:21], v[180:183], v[204:207], v[18:21]
	v_mfma_f32_16x16x32_bf16 v[6:9], v[172:175], v[212:215], v[6:9]
	v_mfma_f32_16x16x32_bf16 v[2:5], v[180:183], v[212:215], v[2:5]
	s_setprio 0
	s_barrier
	s_add_i32 s56, s56, 2
	s_add_u32 s36, s36, 0x100
	s_addc_u32 s37, s37, 0
	s_add_u32 s54, s54, 0x100
	s_addc_u32 s55, s55, 0
	s_cmp_gt_u32 s56, 61
	s_cbranch_scc0 .LBB0_781
	s_and_b64 vcc, exec, s[20:21]
	s_cbranch_vccz .LBB0_784
	s_barrier

; #define PG8_STAGE(bufoff, gbase, voff) do { _Pragma("unroll") for (int _i = 0; _i < 2; ++_i) \
;         __builtin_amdgcn_global_load_lds((const unsigned*)((const char*)(gbase) + (voff)[_i]), (PG8_LAS unsigned*)(lds + (bufoff) + ldsw + _i * 8192), 16, 0, 0); } while (0)
; #define PG8_LDA(dst, b, h) do { _Pragma("unroll") for (int m = 0; m < 4; ++m) _Pragma("unroll") for (int k = 0; k < 2; ++k) dst[m][k] = *(const PG8_LAS bf16x8*)(lds + PG8_SA(b, h) + aoff + m * 2048 + k * 1024); } while (0)
; #define PG8_LDB(dst, b, h) do { _Pragma("unroll") for (int n = 0; n < 2; ++n) _Pragma("unroll") for (int k = 0; k < 2; ++k) dst[n][k] = *(const PG8_LAS bf16x8*)(lds + PG8_SB(b, h) + boff + n * 2048 + k * 1024); } while (0)
; #define PG8_MMA(ai, bj, At, Bt) do { __builtin_amdgcn_s_setprio(1); _Pragma("unroll") for (int m = 0; m < 4; ++m) _Pragma("unroll") for (int n = 0; n < 2; ++n) _Pragma("unroll") for (int k = 0; k < 2; ++k) \
;         acc[ai][bj][m][n] = __builtin_amdgcn_mfma_f32_16x16x32_bf16(Bt[n][k], At[m][k], acc[ai][bj][m][n], 0, 0, 0); __builtin_amdgcn_s_setprio(0); } while (0)
; #define PG8_WAIT_V(n) asm volatile("s_waitcnt vmcnt(" #n ")" ::: "memory")
; #define PG8_WAIT_L(n) asm volatile("s_waitcnt lgkmcnt(" #n ")" ::: "memory")
; #define PG8_BAR __builtin_amdgcn_s_barrier()
; #define PG8_SCHED __builtin_amdgcn_sched_barrier(0)
; template <class Epi, class Sched, bool ALIGN_EPI = false, bool SP2 = false>
; __device__ __forceinline__ void gemm_phase(PG8_LAS unsigned char* lds, const Gemm g, const Sched& S, const Epi& E) {
;     ...
;             const bool last = (t == nt - 2);
;             const char* a1 = cA + (size_t)(t + 1) * kstep;
;             const char* a2 = last ? nA : cA + (size_t)(t + 2) * kstep; const char* b2 = last ? nB : cB + (size_t)(t + 2) * kstep;
;             const char* a3 = a2 + kstep; const char* b3 = b2 + kstep;
;             if (last && has_next) S.a_ready(nxt);
;             if constexpr (SP2) {
;             PG8_LDB(B0, 0, 0); PG8_LDB(B1, 0, 1); PG8_SCHED; PG8_LDA(At, 0, 0); PG8_STAGE(PG8_SA(1, 1), a1 + hstep, voffA);
;             PG8_WAIT_V(8); PG8_WAIT_L(0); PG8_BAR; PG8_MMA(0, 0, At, B0); PG8_MMA(0, 1, At, B1); PG8_BAR; PG8_SCHED;
;             PG8_LDA(At, 0, 1); PG8_STAGE(PG8_SB(0, 0), b2, voffB); PG8_STAGE(PG8_SB(0, 1), b2 + hstep, voffB); PG8_STAGE(PG8_SA(0, 0), a2, voffA);
.LBB0_992:
	ds_read_b128 v[154:157], v150
	ds_read_b128 v[158:161], v150 offset:1024
	ds_read_b128 v[162:165], v150 offset:2048
	ds_read_b128 v[166:169], v150 offset:3072
	ds_read_b128 v[170:173], v151
	ds_read_b128 v[174:177], v151 offset:1024
	ds_read_b128 v[178:181], v151 offset:2048
	ds_read_b128 v[182:185], v151 offset:3072
	s_add_u32 s42, s40, 0xfff00080
	s_addc_u32 s43, s41, -1
	s_cmp_eq_u32 s66, 60
	s_cselect_b32 s45, s31, s43
	s_cselect_b32 s44, s59, s42
	s_cselect_b32 s43, s29, s63
	s_cselect_b32 s42, s61, s62
	v_lshl_add_u64 v[146:147], s[40:41], 0, v[138:139]
	s_add_i32 m0, s39, 0xc000
	ds_read_b128 v[186:189], v152
	ds_read_b128 v[190:193], v152 offset:1024
	ds_read_b128 v[194:197], v152 offset:2048
	ds_read_b128 v[198:201], v152 offset:3072
	ds_read_b128 v[202:205], v152 offset:4096
	ds_read_b128 v[206:209], v152 offset:5120
	ds_read_b128 v[210:213], v152 offset:6144
	ds_read_b128 v[218:221], v152 offset:7168
	global_load_lds_dwordx4 v[146:147], off
	v_lshl_add_u64 v[146:147], s[40:41], 0, v[140:141]
	s_add_i32 m0, s39, 0xe000
	s_nop 0
	global_load_lds_dwordx4 v[146:147], off
	s_waitcnt vmcnt(8)
	s_waitcnt lgkmcnt(0)
	s_barrier
	s_setprio 1
	s_waitcnt lgkmcnt(0)
	v_mfma_f32_16x16x32_bf16 v[126:129], v[154:157], v[186:189], v[126:129]
	v_mfma_f32_16x16x32_bf16 v[122:125], v[162:165], v[186:189], v[122:125]
	v_mfma_f32_16x16x32_bf16 v[114:117], v[154:157], v[194:197], v[114:117]
	v_mfma_f32_16x16x32_bf16 v[106:109], v[162:165], v[194:197], v[106:109]
	v_mfma_f32_16x16x32_bf16 v[98:101], v[154:157], v[202:205], v[98:101]
	v_mfma_f32_16x16x32_bf16 v[90:93], v[162:165], v[202:205], v[90:93]
	v_mfma_f32_16x16x32_bf16 v[82:85], v[154:157], v[210:213], v[82:85]
	v_mfma_f32_16x16x32_bf16 v[74:77], v[162:165], v[210:213], v[74:77]
	v_mfma_f32_16x16x32_bf16 v[126:129], v[158:161], v[190:193], v[126:129]
	v_mfma_f32_16x16x32_bf16 v[122:125], v[166:169], v[190:193], v[122:125]
	v_mfma_f32_16x16x32_bf16 v[114:117], v[158:161], v[198:201], v[114:117]
	v_mfma_f32_16x16x32_bf16 v[106:109], v[166:169], v[198:201], v[106:109]
	v_mfma_f32_16x16x32_bf16 v[98:101], v[158:161], v[206:209], v[98:101]
	v_mfma_f32_16x16x32_bf16 v[90:93], v[166:169], v[206:209], v[90:93]
	v_mfma_f32_16x16x32_bf16 v[82:85], v[158:161], v[218:221], v[82:85]
	v_mfma_f32_16x16x32_bf16 v[74:77], v[166:169], v[218:221], v[74:77]
	v_mfma_f32_16x16x32_bf16 v[118:121], v[170:173], v[186:189], v[118:121]
	v_mfma_f32_16x16x32_bf16 v[110:113], v[178:181], v[186:189], v[110:113]
	v_mfma_f32_16x16x32_bf16 v[102:105], v[170:173], v[194:197], v[102:105]
	v_mfma_f32_16x16x32_bf16 v[94:97], v[178:181], v[194:197], v[94:97]
	v_mfma_f32_16x16x32_bf16 v[86:89], v[170:173], v[202:205], v[86:89]
	v_mfma_f32_16x16x32_bf16 v[78:81], v[178:181], v[202:205], v[78:81]
	v_mfma_f32_16x16x32_bf16 v[70:73], v[170:173], v[210:213], v[70:73]
	v_mfma_f32_16x16x32_bf16 v[66:69], v[178:181], v[210:213], v[66:69]
	v_mfma_f32_16x16x32_bf16 v[118:121], v[174:177], v[190:193], v[118:121]
	v_mfma_f32_16x16x32_bf16 v[110:113], v[182:185], v[190:193], v[110:113]
	v_mfma_f32_16x16x32_bf16 v[102:105], v[174:177], v[198:201], v[102:105]
	v_mfma_f32_16x16x32_bf16 v[94:97], v[182:185], v[198:201], v[94:97]
	v_mfma_f32_16x16x32_bf16 v[86:89], v[174:177], v[206:209], v[86:89]
	v_mfma_f32_16x16x32_bf16 v[78:81], v[182:185], v[206:209], v[78:81]
	v_mfma_f32_16x16x32_bf16 v[70:73], v[174:177], v[218:221], v[70:73]
	v_mfma_f32_16x16x32_bf16 v[66:69], v[182:185], v[218:221], v[66:69]
	s_setprio 0
	s_barrier
	s_add_i32 s67, s52, s33
	v_lshl_add_u64 v[146:147], s[42:43], 0, v[132:133]
	s_mov_b32 m0, s67
	ds_read_b128 v[186:189], v152 offset:16384
	ds_read_b128 v[190:193], v152 offset:17408
	ds_read_b128 v[194:197], v152 offset:18432
	ds_read_b128 v[198:201], v152 offset:19456
	ds_read_b128 v[202:205], v152 offset:20480
	ds_read_b128 v[206:209], v152 offset:21504
	ds_read_b128 v[210:213], v152 offset:22528
	ds_read_b128 v[218:221], v152 offset:23552
	global_load_lds_dwordx4 v[146:147], off
	s_add_i32 m0, s67, 0x2000
	s_add_u32 s68, s42, 0x100000
	v_lshl_add_u64 v[214:215], s[42:43], 0, v[136:137]
	s_addc_u32 s69, s43, 0
	s_add_i32 s67, s53, s33
	global_load_lds_dwordx4 v[214:215], off
	v_lshl_add_u64 v[222:223], s[68:69], 0, v[132:133]
	s_mov_b32 m0, s67
	v_lshl_add_u64 v[224:225], s[44:45], 0, v[134:135]
	global_load_lds_dwordx4 v[222:223], off
	v_lshl_add_u64 v[222:223], s[68:69], 0, v[136:137]
	s_add_i32 m0, s67, 0x2000
	s_nop 0
	global_load_lds_dwordx4 v[222:223], off
	v_lshl_add_u64 v[222:223], s[44:45], 0, v[130:131]
	s_mov_b32 m0, s39
	s_nop 0
	global_load_lds_dwordx4 v[222:223], off
	s_mov_b32 m0, s46
	s_nop 0
	global_load_lds_dwordx4 v[224:225], off
	s_waitcnt vmcnt(8)
	s_waitcnt lgkmcnt(0)
	s_barrier
; #define PG8_STAGE(bufoff, gbase, voff) do { _Pragma("unroll") for (int _i = 0; _i < 2; ++_i) \
;         __builtin_amdgcn_global_load_lds((const unsigned*)((const char*)(gbase) + (voff)[_i]), (PG8_LAS unsigned*)(lds + (bufoff) + ldsw + _i * 8192), 16, 0, 0); } while (0)
; #define PG8_LDA(dst, b, h) do { _Pragma("unroll") for (int m = 0; m < 4; ++m) _Pragma("unroll") for (int k = 0; k < 2; ++k) dst[m][k] = *(const PG8_LAS bf16x8*)(lds + PG8_SA(b, h) + aoff + m * 2048 + k * 1024); } while (0)
; #define PG8_LDB(dst, b, h) do { _Pragma("unroll") for (int n = 0; n < 2; ++n) _Pragma("unroll") for (int k = 0; k < 2; ++k) dst[n][k] = *(const PG8_LAS bf16x8*)(lds + PG8_SB(b, h) + boff + n * 2048 + k * 1024); } while (0)
; #define PG8_MMA(ai, bj, At, Bt) do { __builtin_amdgcn_s_setprio(1); _Pragma("unroll") for (int m = 0; m < 4; ++m) _Pragma("unroll") for (int n = 0; n < 2; ++n) _Pragma("unroll") for (int k = 0; k < 2; ++k) \
;         acc[ai][bj][m][n] = __builtin_amdgcn_mfma_f32_16x16x32_bf16(Bt[n][k], At[m][k], acc[ai][bj][m][n], 0, 0, 0); __builtin_amdgcn_s_setprio(0); } while (0)
; #define PG8_WAIT_V(n) asm volatile("s_waitcnt vmcnt(" #n ")" ::: "memory")
; #define PG8_WAIT_L(n) asm volatile("s_waitcnt lgkmcnt(" #n ")" ::: "memory")
; #define PG8_BAR __builtin_amdgcn_s_barrier()
; #define PG8_SCHED __builtin_amdgcn_sched_barrier(0)
; template <class Epi, class Sched, bool ALIGN_EPI = false, bool SP2 = false>
; __device__ __forceinline__ void gemm_phase(PG8_LAS unsigned char* lds, const Gemm g, const Sched& S, const Epi& E) {
;     ...
;             PG8_WAIT_V(8); PG8_WAIT_L(0); PG8_BAR; PG8_MMA(1, 0, At, B0); PG8_MMA(1, 1, At, B1); PG8_BAR; PG8_SCHED;
;             PG8_LDB(B0, 1, 0); PG8_LDB(B1, 1, 1); PG8_SCHED; PG8_LDA(At, 1, 0); PG8_STAGE(PG8_SA(0, 1), a2 + hstep, voffA);
;             PG8_WAIT_V(8); PG8_WAIT_L(0); PG8_BAR; PG8_MMA(0, 0, At, B0); PG8_MMA(0, 1, At, B1); PG8_BAR; PG8_SCHED;
	s_setprio 1
	s_waitcnt lgkmcnt(0)
	v_mfma_f32_16x16x32_bf16 v[62:65], v[154:157], v[186:189], v[62:65]
	v_mfma_f32_16x16x32_bf16 v[58:61], v[162:165], v[186:189], v[58:61]
	v_mfma_f32_16x16x32_bf16 v[50:53], v[154:157], v[194:197], v[50:53]
	v_mfma_f32_16x16x32_bf16 v[42:45], v[162:165], v[194:197], v[42:45]
	v_mfma_f32_16x16x32_bf16 v[34:37], v[154:157], v[202:205], v[34:37]
	v_mfma_f32_16x16x32_bf16 v[26:29], v[162:165], v[202:205], v[26:29]
	v_mfma_f32_16x16x32_bf16 v[18:21], v[154:157], v[210:213], v[18:21]
	v_mfma_f32_16x16x32_bf16 v[10:13], v[162:165], v[210:213], v[10:13]
	v_mfma_f32_16x16x32_bf16 v[62:65], v[158:161], v[190:193], v[62:65]
	v_mfma_f32_16x16x32_bf16 v[58:61], v[166:169], v[190:193], v[58:61]
	v_mfma_f32_16x16x32_bf16 v[50:53], v[158:161], v[198:201], v[50:53]
	v_mfma_f32_16x16x32_bf16 v[42:45], v[166:169], v[198:201], v[42:45]
	v_mfma_f32_16x16x32_bf16 v[34:37], v[158:161], v[206:209], v[34:37]
	v_mfma_f32_16x16x32_bf16 v[26:29], v[166:169], v[206:209], v[26:29]
	v_mfma_f32_16x16x32_bf16 v[18:21], v[158:161], v[218:221], v[18:21]
	v_mfma_f32_16x16x32_bf16 v[10:13], v[166:169], v[218:221], v[10:13]
	v_mfma_f32_16x16x32_bf16 v[54:57], v[170:173], v[186:189], v[54:57]
	v_mfma_f32_16x16x32_bf16 v[46:49], v[178:181], v[186:189], v[46:49]
	v_mfma_f32_16x16x32_bf16 v[38:41], v[170:173], v[194:197], v[38:41]
	v_mfma_f32_16x16x32_bf16 v[30:33], v[178:181], v[194:197], v[30:33]
	v_mfma_f32_16x16x32_bf16 v[22:25], v[170:173], v[202:205], v[22:25]
	v_mfma_f32_16x16x32_bf16 v[14:17], v[178:181], v[202:205], v[14:17]
	v_mfma_f32_16x16x32_bf16 v[6:9], v[170:173], v[210:213], v[6:9]
	v_mfma_f32_16x16x32_bf16 v[2:5], v[178:181], v[210:213], v[2:5]
	v_mfma_f32_16x16x32_bf16 v[54:57], v[174:177], v[190:193], v[54:57]
	v_mfma_f32_16x16x32_bf16 v[46:49], v[182:185], v[190:193], v[46:49]
	v_mfma_f32_16x16x32_bf16 v[38:41], v[174:177], v[198:201], v[38:41]
	v_mfma_f32_16x16x32_bf16 v[30:33], v[182:185], v[198:201], v[30:33]
	v_mfma_f32_16x16x32_bf16 v[22:25], v[174:177], v[206:209], v[22:25]
	v_mfma_f32_16x16x32_bf16 v[14:17], v[182:185], v[206:209], v[14:17]
	v_mfma_f32_16x16x32_bf16 v[6:9], v[174:177], v[218:221], v[6:9]
	v_mfma_f32_16x16x32_bf16 v[2:5], v[182:185], v[218:221], v[2:5]
	s_setprio 0
	s_barrier
	s_add_i32 s67, 0, 0x18000
	v_add_u32_e32 v153, s67, v148
	s_add_i32 s68, 0, 0x1c000
	ds_read_b128 v[154:157], v153
	ds_read_b128 v[158:161], v153 offset:1024
	ds_read_b128 v[162:165], v153 offset:2048
	ds_read_b128 v[166:169], v153 offset:3072
	v_add_u32_e32 v153, s68, v148
	ds_read_b128 v[170:173], v153
	ds_read_b128 v[174:177], v153 offset:1024
	ds_read_b128 v[178:181], v153 offset:2048
	ds_read_b128 v[182:185], v153 offset:3072
	s_add_u32 s44, s44, 0x100000
	s_addc_u32 s45, s45, 0
	s_mov_b32 m0, s47
	v_lshl_add_u64 v[226:227], s[44:45], 0, v[130:131]
	ds_read_b128 v[186:189], v152 offset:32768
	ds_read_b128 v[190:193], v152 offset:33792
	ds_read_b128 v[194:197], v152 offset:34816
	ds_read_b128 v[198:201], v152 offset:35840
	ds_read_b128 v[202:205], v152 offset:36864
	ds_read_b128 v[206:209], v152 offset:37888
	ds_read_b128 v[210:213], v152 offset:38912
	ds_read_b128 v[218:221], v152 offset:39936
	global_load_lds_dwordx4 v[226:227], off
	v_lshl_add_u64 v[226:227], s[44:45], 0, v[134:135]
	s_mov_b32 m0, s48
	s_nop 0
	global_load_lds_dwordx4 v[226:227], off
	s_waitcnt vmcnt(8)
	s_waitcnt lgkmcnt(0)
	s_barrier
	s_setprio 1
	s_waitcnt lgkmcnt(0)
	v_mfma_f32_16x16x32_bf16 v[126:129], v[154:157], v[186:189], v[126:129]
	v_mfma_f32_16x16x32_bf16 v[122:125], v[162:165], v[186:189], v[122:125]
	v_mfma_f32_16x16x32_bf16 v[114:117], v[154:157], v[194:197], v[114:117]
	v_mfma_f32_16x16x32_bf16 v[106:109], v[162:165], v[194:197], v[106:109]
	v_mfma_f32_16x16x32_bf16 v[98:101], v[154:157], v[202:205], v[98:101]
	v_mfma_f32_16x16x32_bf16 v[90:93], v[162:165], v[202:205], v[90:93]
	v_mfma_f32_16x16x32_bf16 v[82:85], v[154:157], v[210:213], v[82:85]
	v_mfma_f32_16x16x32_bf16 v[74:77], v[162:165], v[210:213], v[74:77]
	v_mfma_f32_16x16x32_bf16 v[126:129], v[158:161], v[190:193], v[126:129]
	v_mfma_f32_16x16x32_bf16 v[122:125], v[166:169], v[190:193], v[122:125]
	v_mfma_f32_16x16x32_bf16 v[114:117], v[158:161], v[198:201], v[114:117]
	v_mfma_f32_16x16x32_bf16 v[106:109], v[166:169], v[198:201], v[106:109]
	v_mfma_f32_16x16x32_bf16 v[98:101], v[158:161], v[206:209], v[98:101]
	v_mfma_f32_16x16x32_bf16 v[90:93], v[166:169], v[206:209], v[90:93]
	v_mfma_f32_16x16x32_bf16 v[82:85], v[158:161], v[218:221], v[82:85]
	v_mfma_f32_16x16x32_bf16 v[74:77], v[166:169], v[218:221], v[74:77]
	v_mfma_f32_16x16x32_bf16 v[118:121], v[170:173], v[186:189], v[118:121]
	v_mfma_f32_16x16x32_bf16 v[110:113], v[178:181], v[186:189], v[110:113]
	v_mfma_f32_16x16x32_bf16 v[102:105], v[170:173], v[194:197], v[102:105]
	v_mfma_f32_16x16x32_bf16 v[94:97], v[178:181], v[194:197], v[94:97]
	v_mfma_f32_16x16x32_bf16 v[86:89], v[170:173], v[202:205], v[86:89]
	v_mfma_f32_16x16x32_bf16 v[78:81], v[178:181], v[202:205], v[78:81]
	v_mfma_f32_16x16x32_bf16 v[70:73], v[170:173], v[210:213], v[70:73]
	v_mfma_f32_16x16x32_bf16 v[66:69], v[178:181], v[210:213], v[66:69]
	v_mfma_f32_16x16x32_bf16 v[118:121], v[174:177], v[190:193], v[118:121]
	v_mfma_f32_16x16x32_bf16 v[110:113], v[182:185], v[190:193], v[110:113]
	v_mfma_f32_16x16x32_bf16 v[102:105], v[174:177], v[198:201], v[102:105]
	v_mfma_f32_16x16x32_bf16 v[94:97], v[182:185], v[198:201], v[94:97]
	v_mfma_f32_16x16x32_bf16 v[86:89], v[174:177], v[206:209], v[86:89]
	v_mfma_f32_16x16x32_bf16 v[78:81], v[182:185], v[206:209], v[78:81]
	v_mfma_f32_16x16x32_bf16 v[70:73], v[174:177], v[218:221], v[70:73]
	v_mfma_f32_16x16x32_bf16 v[66:69], v[182:185], v[218:221], v[66:69]
	s_setprio 0
	s_barrier
; #define PG8_STAGE(bufoff, gbase, voff) do { _Pragma("unroll") for (int _i = 0; _i < 2; ++_i) \
;         __builtin_amdgcn_global_load_lds((const unsigned*)((const char*)(gbase) + (voff)[_i]), (PG8_LAS unsigned*)(lds + (bufoff) + ldsw + _i * 8192), 16, 0, 0); } while (0)
; #define PG8_LDA(dst, b, h) do { _Pragma("unroll") for (int m = 0; m < 4; ++m) _Pragma("unroll") for (int k = 0; k < 2; ++k) dst[m][k] = *(const PG8_LAS bf16x8*)(lds + PG8_SA(b, h) + aoff + m * 2048 + k * 1024); } while (0)
; #define PG8_MMA(ai, bj, At, Bt) do { __builtin_amdgcn_s_setprio(1); _Pragma("unroll") for (int m = 0; m < 4; ++m) _Pragma("unroll") for (int n = 0; n < 2; ++n) _Pragma("unroll") for (int k = 0; k < 2; ++k) \
;         acc[ai][bj][m][n] = __builtin_amdgcn_mfma_f32_16x16x32_bf16(Bt[n][k], At[m][k], acc[ai][bj][m][n], 0, 0, 0); __builtin_amdgcn_s_setprio(0); } while (0)
; #define PG8_WAIT_V(n) asm volatile("s_waitcnt vmcnt(" #n ")" ::: "memory")
; #define PG8_WAIT_L(n) asm volatile("s_waitcnt lgkmcnt(" #n ")" ::: "memory")
; #define PG8_BAR __builtin_amdgcn_s_barrier()
; #define PG8_SCHED __builtin_amdgcn_sched_barrier(0)
; template <class Epi, class Sched, bool ALIGN_EPI = false, bool SP2 = false>
; __device__ __forceinline__ void gemm_phase(PG8_LAS unsigned char* lds, const Gemm g, const Sched& S, const Epi& E) {
;     ...
;             PG8_LDA(At, 1, 1); PG8_STAGE(PG8_SB(1, 0), b3, voffB); PG8_STAGE(PG8_SB(1, 1), b3 + hstep, voffB); PG8_STAGE(PG8_SA(1, 0), a3, voffA);
;             PG8_WAIT_V(8); PG8_WAIT_L(0); PG8_BAR; PG8_MMA(1, 0, At, B0); PG8_MMA(1, 1, At, B1); PG8_BAR; PG8_SCHED;
;     ...
;         }
;         if constexpr (ALIGN_EPI) { if (wr == 0) PG8_BAR; }
	s_add_i32 s44, s67, s33
	v_lshl_add_u64 v[146:147], v[146:147], 0, s[12:13]
	s_mov_b32 m0, s44
	ds_read_b128 v[186:189], v152 offset:49152
	ds_read_b128 v[190:193], v152 offset:50176
	ds_read_b128 v[194:197], v152 offset:51200
	ds_read_b128 v[198:201], v152 offset:52224
	ds_read_b128 v[202:205], v152 offset:53248
	ds_read_b128 v[206:209], v152 offset:54272
	ds_read_b128 v[210:213], v152 offset:55296
	ds_read_b128 v[218:221], v152 offset:56320
	global_load_lds_dwordx4 v[146:147], off
	s_add_i32 m0, s44, 0x2000
	s_add_u32 s42, s42, 0x100080
	v_lshl_add_u64 v[146:147], v[214:215], 0, s[12:13]
	s_addc_u32 s43, s43, 0
	s_add_i32 s44, s68, s33
	global_load_lds_dwordx4 v[146:147], off
	v_lshl_add_u64 v[146:147], s[42:43], 0, v[132:133]
	s_mov_b32 m0, s44
	s_nop 0
	global_load_lds_dwordx4 v[146:147], off
	v_lshl_add_u64 v[146:147], s[42:43], 0, v[136:137]
	s_add_i32 m0, s44, 0x2000
	s_nop 0
	global_load_lds_dwordx4 v[146:147], off
	v_lshl_add_u64 v[146:147], v[222:223], 0, s[12:13]
	s_mov_b32 m0, s50
	s_nop 0
	global_load_lds_dwordx4 v[146:147], off
	v_lshl_add_u64 v[146:147], v[224:225], 0, s[12:13]
	s_mov_b32 m0, s51
	s_nop 0
	global_load_lds_dwordx4 v[146:147], off
	s_waitcnt vmcnt(8)
	s_waitcnt lgkmcnt(0)
	s_barrier
	s_setprio 1
	s_waitcnt lgkmcnt(0)
	v_mfma_f32_16x16x32_bf16 v[62:65], v[154:157], v[186:189], v[62:65]
	v_mfma_f32_16x16x32_bf16 v[58:61], v[162:165], v[186:189], v[58:61]
	v_mfma_f32_16x16x32_bf16 v[50:53], v[154:157], v[194:197], v[50:53]
	v_mfma_f32_16x16x32_bf16 v[42:45], v[162:165], v[194:197], v[42:45]
	v_mfma_f32_16x16x32_bf16 v[34:37], v[154:157], v[202:205], v[34:37]
	v_mfma_f32_16x16x32_bf16 v[26:29], v[162:165], v[202:205], v[26:29]
	v_mfma_f32_16x16x32_bf16 v[18:21], v[154:157], v[210:213], v[18:21]
	v_mfma_f32_16x16x32_bf16 v[10:13], v[162:165], v[210:213], v[10:13]
	v_mfma_f32_16x16x32_bf16 v[62:65], v[158:161], v[190:193], v[62:65]
	v_mfma_f32_16x16x32_bf16 v[58:61], v[166:169], v[190:193], v[58:61]
	v_mfma_f32_16x16x32_bf16 v[50:53], v[158:161], v[198:201], v[50:53]
	v_mfma_f32_16x16x32_bf16 v[42:45], v[166:169], v[198:201], v[42:45]
	v_mfma_f32_16x16x32_bf16 v[34:37], v[158:161], v[206:209], v[34:37]
	v_mfma_f32_16x16x32_bf16 v[26:29], v[166:169], v[206:209], v[26:29]
	v_mfma_f32_16x16x32_bf16 v[18:21], v[158:161], v[218:221], v[18:21]
	v_mfma_f32_16x16x32_bf16 v[10:13], v[166:169], v[218:221], v[10:13]
	v_mfma_f32_16x16x32_bf16 v[54:57], v[170:173], v[186:189], v[54:57]
	v_mfma_f32_16x16x32_bf16 v[46:49], v[178:181], v[186:189], v[46:49]
	v_mfma_f32_16x16x32_bf16 v[38:41], v[170:173], v[194:197], v[38:41]
	v_mfma_f32_16x16x32_bf16 v[30:33], v[178:181], v[194:197], v[30:33]
	v_mfma_f32_16x16x32_bf16 v[22:25], v[170:173], v[202:205], v[22:25]
	v_mfma_f32_16x16x32_bf16 v[14:17], v[178:181], v[202:205], v[14:17]
	v_mfma_f32_16x16x32_bf16 v[6:9], v[170:173], v[210:213], v[6:9]
	v_mfma_f32_16x16x32_bf16 v[2:5], v[178:181], v[210:213], v[2:5]
	v_mfma_f32_16x16x32_bf16 v[54:57], v[174:177], v[190:193], v[54:57]
	v_mfma_f32_16x16x32_bf16 v[46:49], v[182:185], v[190:193], v[46:49]
	v_mfma_f32_16x16x32_bf16 v[38:41], v[174:177], v[198:201], v[38:41]
	v_mfma_f32_16x16x32_bf16 v[30:33], v[182:185], v[198:201], v[30:33]
	v_mfma_f32_16x16x32_bf16 v[22:25], v[174:177], v[206:209], v[22:25]
	v_mfma_f32_16x16x32_bf16 v[14:17], v[182:185], v[206:209], v[14:17]
	v_mfma_f32_16x16x32_bf16 v[6:9], v[174:177], v[218:221], v[6:9]
	v_mfma_f32_16x16x32_bf16 v[2:5], v[182:185], v[218:221], v[2:5]
	s_setprio 0
	s_barrier
	s_add_i32 s66, s66, 2
	s_add_u32 s40, s40, 0x100
	s_addc_u32 s41, s41, 0
	s_add_u32 s62, s62, 0x100
	s_addc_u32 s63, s63, 0
	s_cmp_gt_u32 s66, 61
	s_cbranch_scc0 .LBB0_992
	s_and_b64 vcc, exec, s[14:15]
	s_cbranch_vccz .LBB0_995
	s_barrier

; #define PG8_STAGE(bufoff, gbase, voff) do { _Pragma("unroll") for (int _i = 0; _i < 2; ++_i) \
;         __builtin_amdgcn_global_load_lds((const unsigned*)((const char*)(gbase) + (voff)[_i]), (PG8_LAS unsigned*)(lds + (bufoff) + ldsw + _i * 8192), 16, 0, 0); } while (0)
; #define PG8_LDA(dst, b, h) do { _Pragma("unroll") for (int m = 0; m < 4; ++m) _Pragma("unroll") for (int k = 0; k < 2; ++k) dst[m][k] = *(const PG8_LAS bf16x8*)(lds + PG8_SA(b, h) + aoff + m * 2048 + k * 1024); } while (0)
; #define PG8_LDB(dst, b, h) do { _Pragma("unroll") for (int n = 0; n < 2; ++n) _Pragma("unroll") for (int k = 0; k < 2; ++k) dst[n][k] = *(const PG8_LAS bf16x8*)(lds + PG8_SB(b, h) + boff + n * 2048 + k * 1024); } while (0)
; #define PG8_MMA(ai, bj, At, Bt) do { __builtin_amdgcn_s_setprio(1); _Pragma("unroll") for (int m = 0; m < 4; ++m) _Pragma("unroll") for (int n = 0; n < 2; ++n) _Pragma("unroll") for (int k = 0; k < 2; ++k) \
;         acc[ai][bj][m][n] = __builtin_amdgcn_mfma_f32_16x16x32_bf16(Bt[n][k], At[m][k], acc[ai][bj][m][n], 0, 0, 0); __builtin_amdgcn_s_setprio(0); } while (0)
; #define PG8_WAIT_V(n) asm volatile("s_waitcnt vmcnt(" #n ")" ::: "memory")
; #define PG8_WAIT_L(n) asm volatile("s_waitcnt lgkmcnt(" #n ")" ::: "memory")
; #define PG8_BAR __builtin_amdgcn_s_barrier()
; #define PG8_SCHED __builtin_amdgcn_sched_barrier(0)
; template <class Epi, class Sched, bool ALIGN_EPI = false, bool SP2 = false>
; __device__ __forceinline__ void gemm_phase(PG8_LAS unsigned char* lds, const Gemm g, const Sched& S, const Epi& E) {
;     ...
;             const bool last = (t == nt - 2);
;             const char* a1 = cA + (size_t)(t + 1) * kstep;
;             const char* a2 = last ? nA : cA + (size_t)(t + 2) * kstep; const char* b2 = last ? nB : cB + (size_t)(t + 2) * kstep;
;             const char* a3 = a2 + kstep; const char* b3 = b2 + kstep;
;             if (last && has_next) S.a_ready(nxt);
;             if constexpr (SP2) {
;             PG8_LDB(B0, 0, 0); PG8_LDB(B1, 0, 1); PG8_SCHED; PG8_LDA(At, 0, 0); PG8_STAGE(PG8_SA(1, 1), a1 + hstep, voffA);
;             PG8_WAIT_V(8); PG8_WAIT_L(0); PG8_BAR; PG8_MMA(0, 0, At, B0); PG8_MMA(0, 1, At, B1); PG8_BAR; PG8_SCHED;
;             PG8_LDA(At, 0, 1); PG8_STAGE(PG8_SB(0, 0), b2, voffB); PG8_STAGE(PG8_SB(0, 1), b2 + hstep, voffB); PG8_STAGE(PG8_SA(0, 0), a2, voffA);
.LBB0_1089:
	ds_read_b128 v[146:149], v152
	ds_read_b128 v[156:159], v152 offset:1024
	ds_read_b128 v[160:163], v152 offset:2048
	ds_read_b128 v[164:167], v152 offset:3072
	ds_read_b128 v[168:171], v153
	ds_read_b128 v[172:175], v153 offset:1024
	ds_read_b128 v[176:179], v153 offset:2048
	ds_read_b128 v[180:183], v153 offset:3072
	s_add_u32 s38, s36, 0xffc00080
	s_addc_u32 s39, s37, -1
	s_cmpk_eq_i32 s54, 0xfc
	s_cselect_b32 s41, s25, s39
	s_cselect_b32 s40, s31, s38
	s_cselect_b32 s39, s23, s53
	s_cselect_b32 s38, s35, s52
	v_lshl_add_u64 v[218:219], s[36:37], 0, v[138:139]
	s_add_i32 m0, s42, 0xc000
	ds_read_b128 v[184:187], v154
	ds_read_b128 v[188:191], v154 offset:1024
	ds_read_b128 v[192:195], v154 offset:2048
	ds_read_b128 v[196:199], v154 offset:3072
	ds_read_b128 v[200:203], v154 offset:4096
	ds_read_b128 v[204:207], v154 offset:5120
	ds_read_b128 v[208:211], v154 offset:6144
	ds_read_b128 v[212:215], v154 offset:7168
	global_load_lds_dwordx4 v[218:219], off
	v_lshl_add_u64 v[218:219], s[36:37], 0, v[140:141]
	s_add_i32 m0, s42, 0xe000
	s_nop 0
	global_load_lds_dwordx4 v[218:219], off
	s_waitcnt vmcnt(8)
	s_waitcnt lgkmcnt(0)
	s_barrier
	s_setprio 1
	s_waitcnt lgkmcnt(0)
	v_mfma_f32_16x16x32_bf16 v[126:129], v[146:149], v[184:187], v[126:129]
	v_mfma_f32_16x16x32_bf16 v[122:125], v[160:163], v[184:187], v[122:125]
	v_mfma_f32_16x16x32_bf16 v[110:113], v[146:149], v[192:195], v[110:113]
	v_mfma_f32_16x16x32_bf16 v[106:109], v[160:163], v[192:195], v[106:109]
	v_mfma_f32_16x16x32_bf16 v[94:97], v[146:149], v[200:203], v[94:97]
	v_mfma_f32_16x16x32_bf16 v[90:93], v[160:163], v[200:203], v[90:93]
	v_mfma_f32_16x16x32_bf16 v[78:81], v[146:149], v[208:211], v[78:81]
	v_mfma_f32_16x16x32_bf16 v[74:77], v[160:163], v[208:211], v[74:77]
	v_mfma_f32_16x16x32_bf16 v[126:129], v[156:159], v[188:191], v[126:129]
	v_mfma_f32_16x16x32_bf16 v[122:125], v[164:167], v[188:191], v[122:125]
	v_mfma_f32_16x16x32_bf16 v[110:113], v[156:159], v[196:199], v[110:113]
	v_mfma_f32_16x16x32_bf16 v[106:109], v[164:167], v[196:199], v[106:109]
	v_mfma_f32_16x16x32_bf16 v[94:97], v[156:159], v[204:207], v[94:97]
	v_mfma_f32_16x16x32_bf16 v[90:93], v[164:167], v[204:207], v[90:93]
	v_mfma_f32_16x16x32_bf16 v[78:81], v[156:159], v[212:215], v[78:81]
	v_mfma_f32_16x16x32_bf16 v[74:77], v[164:167], v[212:215], v[74:77]
	v_mfma_f32_16x16x32_bf16 v[118:121], v[168:171], v[184:187], v[118:121]
	v_mfma_f32_16x16x32_bf16 v[114:117], v[176:179], v[184:187], v[114:117]
	v_mfma_f32_16x16x32_bf16 v[102:105], v[168:171], v[192:195], v[102:105]
	v_mfma_f32_16x16x32_bf16 v[98:101], v[176:179], v[192:195], v[98:101]
	v_mfma_f32_16x16x32_bf16 v[86:89], v[168:171], v[200:203], v[86:89]
	v_mfma_f32_16x16x32_bf16 v[82:85], v[176:179], v[200:203], v[82:85]
	v_mfma_f32_16x16x32_bf16 v[70:73], v[168:171], v[208:211], v[70:73]
	v_mfma_f32_16x16x32_bf16 v[66:69], v[176:179], v[208:211], v[66:69]
	v_mfma_f32_16x16x32_bf16 v[118:121], v[172:175], v[188:191], v[118:121]
	v_mfma_f32_16x16x32_bf16 v[114:117], v[180:183], v[188:191], v[114:117]
	v_mfma_f32_16x16x32_bf16 v[102:105], v[172:175], v[196:199], v[102:105]
	v_mfma_f32_16x16x32_bf16 v[98:101], v[180:183], v[196:199], v[98:101]
	v_mfma_f32_16x16x32_bf16 v[86:89], v[172:175], v[204:207], v[86:89]
	v_mfma_f32_16x16x32_bf16 v[82:85], v[180:183], v[204:207], v[82:85]
	v_mfma_f32_16x16x32_bf16 v[70:73], v[172:175], v[212:215], v[70:73]
	v_mfma_f32_16x16x32_bf16 v[66:69], v[180:183], v[212:215], v[66:69]
	s_setprio 0
	s_barrier
	s_add_i32 s55, s50, s33
	v_lshl_add_u64 v[218:219], s[38:39], 0, v[132:133]
	s_mov_b32 m0, s55
	ds_read_b128 v[184:187], v154 offset:16384
	ds_read_b128 v[188:191], v154 offset:17408
	ds_read_b128 v[192:195], v154 offset:18432
	ds_read_b128 v[196:199], v154 offset:19456
	ds_read_b128 v[200:203], v154 offset:20480
	ds_read_b128 v[204:207], v154 offset:21504
	ds_read_b128 v[208:211], v154 offset:22528
	ds_read_b128 v[212:215], v154 offset:23552
	global_load_lds_dwordx4 v[218:219], off
	s_add_i32 m0, s55, 0x2000
	s_add_u32 s56, s38, 0x400000
	v_lshl_add_u64 v[220:221], s[38:39], 0, v[136:137]
	s_addc_u32 s57, s39, 0
	s_add_i32 s55, s51, s33
	global_load_lds_dwordx4 v[220:221], off
	v_lshl_add_u64 v[222:223], s[56:57], 0, v[132:133]
	s_mov_b32 m0, s55
	v_lshl_add_u64 v[224:225], s[40:41], 0, v[134:135]
	global_load_lds_dwordx4 v[222:223], off
	v_lshl_add_u64 v[222:223], s[56:57], 0, v[136:137]
	s_add_i32 m0, s55, 0x2000
	s_nop 0
	global_load_lds_dwordx4 v[222:223], off
	v_lshl_add_u64 v[222:223], s[40:41], 0, v[130:131]
	s_mov_b32 m0, s42
	s_nop 0
	global_load_lds_dwordx4 v[222:223], off
	s_mov_b32 m0, s43
	s_nop 0
	global_load_lds_dwordx4 v[224:225], off
	s_waitcnt vmcnt(8)
	s_waitcnt lgkmcnt(0)
	s_barrier
; #define PG8_STAGE(bufoff, gbase, voff) do { _Pragma("unroll") for (int _i = 0; _i < 2; ++_i) \
;         __builtin_amdgcn_global_load_lds((const unsigned*)((const char*)(gbase) + (voff)[_i]), (PG8_LAS unsigned*)(lds + (bufoff) + ldsw + _i * 8192), 16, 0, 0); } while (0)
; #define PG8_LDA(dst, b, h) do { _Pragma("unroll") for (int m = 0; m < 4; ++m) _Pragma("unroll") for (int k = 0; k < 2; ++k) dst[m][k] = *(const PG8_LAS bf16x8*)(lds + PG8_SA(b, h) + aoff + m * 2048 + k * 1024); } while (0)
; #define PG8_LDB(dst, b, h) do { _Pragma("unroll") for (int n = 0; n < 2; ++n) _Pragma("unroll") for (int k = 0; k < 2; ++k) dst[n][k] = *(const PG8_LAS bf16x8*)(lds + PG8_SB(b, h) + boff + n * 2048 + k * 1024); } while (0)
; #define PG8_MMA(ai, bj, At, Bt) do { __builtin_amdgcn_s_setprio(1); _Pragma("unroll") for (int m = 0; m < 4; ++m) _Pragma("unroll") for (int n = 0; n < 2; ++n) _Pragma("unroll") for (int k = 0; k < 2; ++k) \
;         acc[ai][bj][m][n] = __builtin_amdgcn_mfma_f32_16x16x32_bf16(Bt[n][k], At[m][k], acc[ai][bj][m][n], 0, 0, 0); __builtin_amdgcn_s_setprio(0); } while (0)
; #define PG8_WAIT_V(n) asm volatile("s_waitcnt vmcnt(" #n ")" ::: "memory")
; #define PG8_WAIT_L(n) asm volatile("s_waitcnt lgkmcnt(" #n ")" ::: "memory")
; #define PG8_BAR __builtin_amdgcn_s_barrier()
; #define PG8_SCHED __builtin_amdgcn_sched_barrier(0)
; template <class Epi, class Sched, bool ALIGN_EPI = false, bool SP2 = false>
; __device__ __forceinline__ void gemm_phase(PG8_LAS unsigned char* lds, const Gemm g, const Sched& S, const Epi& E) {
;     ...
;             PG8_WAIT_V(8); PG8_WAIT_L(0); PG8_BAR; PG8_MMA(1, 0, At, B0); PG8_MMA(1, 1, At, B1); PG8_BAR; PG8_SCHED;
;             PG8_LDB(B0, 1, 0); PG8_LDB(B1, 1, 1); PG8_SCHED; PG8_LDA(At, 1, 0); PG8_STAGE(PG8_SA(0, 1), a2 + hstep, voffA);
;             PG8_WAIT_V(8); PG8_WAIT_L(0); PG8_BAR; PG8_MMA(0, 0, At, B0); PG8_MMA(0, 1, At, B1); PG8_BAR; PG8_SCHED;
	s_setprio 1
	s_waitcnt lgkmcnt(0)
	v_mfma_f32_16x16x32_bf16 v[62:65], v[146:149], v[184:187], v[62:65]
	v_mfma_f32_16x16x32_bf16 v[58:61], v[160:163], v[184:187], v[58:61]
	v_mfma_f32_16x16x32_bf16 v[46:49], v[146:149], v[192:195], v[46:49]
	v_mfma_f32_16x16x32_bf16 v[42:45], v[160:163], v[192:195], v[42:45]
	v_mfma_f32_16x16x32_bf16 v[30:33], v[146:149], v[200:203], v[30:33]
	v_mfma_f32_16x16x32_bf16 v[26:29], v[160:163], v[200:203], v[26:29]
	v_mfma_f32_16x16x32_bf16 v[14:17], v[146:149], v[208:211], v[14:17]
	v_mfma_f32_16x16x32_bf16 v[10:13], v[160:163], v[208:211], v[10:13]
	v_mfma_f32_16x16x32_bf16 v[62:65], v[156:159], v[188:191], v[62:65]
	v_mfma_f32_16x16x32_bf16 v[58:61], v[164:167], v[188:191], v[58:61]
	v_mfma_f32_16x16x32_bf16 v[46:49], v[156:159], v[196:199], v[46:49]
	v_mfma_f32_16x16x32_bf16 v[42:45], v[164:167], v[196:199], v[42:45]
	v_mfma_f32_16x16x32_bf16 v[30:33], v[156:159], v[204:207], v[30:33]
	v_mfma_f32_16x16x32_bf16 v[26:29], v[164:167], v[204:207], v[26:29]
	v_mfma_f32_16x16x32_bf16 v[14:17], v[156:159], v[212:215], v[14:17]
	v_mfma_f32_16x16x32_bf16 v[10:13], v[164:167], v[212:215], v[10:13]
	v_mfma_f32_16x16x32_bf16 v[54:57], v[168:171], v[184:187], v[54:57]
	v_mfma_f32_16x16x32_bf16 v[50:53], v[176:179], v[184:187], v[50:53]
	v_mfma_f32_16x16x32_bf16 v[38:41], v[168:171], v[192:195], v[38:41]
	v_mfma_f32_16x16x32_bf16 v[34:37], v[176:179], v[192:195], v[34:37]
	v_mfma_f32_16x16x32_bf16 v[22:25], v[168:171], v[200:203], v[22:25]
	v_mfma_f32_16x16x32_bf16 v[18:21], v[176:179], v[200:203], v[18:21]
	v_mfma_f32_16x16x32_bf16 v[6:9], v[168:171], v[208:211], v[6:9]
	v_mfma_f32_16x16x32_bf16 v[2:5], v[176:179], v[208:211], v[2:5]
	v_mfma_f32_16x16x32_bf16 v[54:57], v[172:175], v[188:191], v[54:57]
	v_mfma_f32_16x16x32_bf16 v[50:53], v[180:183], v[188:191], v[50:53]
	v_mfma_f32_16x16x32_bf16 v[38:41], v[172:175], v[196:199], v[38:41]
	v_mfma_f32_16x16x32_bf16 v[34:37], v[180:183], v[196:199], v[34:37]
	v_mfma_f32_16x16x32_bf16 v[22:25], v[172:175], v[204:207], v[22:25]
	v_mfma_f32_16x16x32_bf16 v[18:21], v[180:183], v[204:207], v[18:21]
	v_mfma_f32_16x16x32_bf16 v[6:9], v[172:175], v[212:215], v[6:9]
	v_mfma_f32_16x16x32_bf16 v[2:5], v[180:183], v[212:215], v[2:5]
	s_setprio 0
	s_barrier
	s_add_i32 s55, 0, 0x18000
	s_add_i32 s56, 0, 0x1c000
	v_add_u32_e32 v164, s55, v150
	v_add_u32_e32 v180, s56, v150
	ds_read_b128 v[146:149], v164
	ds_read_b128 v[156:159], v164 offset:1024
	ds_read_b128 v[160:163], v164 offset:2048
	ds_read_b128 v[164:167], v164 offset:3072
	ds_read_b128 v[168:171], v180
	ds_read_b128 v[172:175], v180 offset:1024
	ds_read_b128 v[176:179], v180 offset:2048
	ds_read_b128 v[180:183], v180 offset:3072
	s_add_u32 s40, s40, 0x400000
	s_addc_u32 s41, s41, 0
	s_mov_b32 m0, s44
	v_lshl_add_u64 v[226:227], s[40:41], 0, v[130:131]
	ds_read_b128 v[184:187], v154 offset:32768
	ds_read_b128 v[188:191], v154 offset:33792
	ds_read_b128 v[192:195], v154 offset:34816
	ds_read_b128 v[196:199], v154 offset:35840
	ds_read_b128 v[200:203], v154 offset:36864
	ds_read_b128 v[204:207], v154 offset:37888
	ds_read_b128 v[208:211], v154 offset:38912
	ds_read_b128 v[212:215], v154 offset:39936
	global_load_lds_dwordx4 v[226:227], off
	v_lshl_add_u64 v[226:227], s[40:41], 0, v[134:135]
	s_mov_b32 m0, s45
	s_nop 0
	global_load_lds_dwordx4 v[226:227], off
	s_waitcnt vmcnt(8)
	s_waitcnt lgkmcnt(0)
	s_barrier
	s_setprio 1
	s_waitcnt lgkmcnt(0)
	v_mfma_f32_16x16x32_bf16 v[126:129], v[146:149], v[184:187], v[126:129]
	v_mfma_f32_16x16x32_bf16 v[122:125], v[160:163], v[184:187], v[122:125]
	v_mfma_f32_16x16x32_bf16 v[110:113], v[146:149], v[192:195], v[110:113]
	v_mfma_f32_16x16x32_bf16 v[106:109], v[160:163], v[192:195], v[106:109]
	v_mfma_f32_16x16x32_bf16 v[94:97], v[146:149], v[200:203], v[94:97]
	v_mfma_f32_16x16x32_bf16 v[90:93], v[160:163], v[200:203], v[90:93]
	v_mfma_f32_16x16x32_bf16 v[78:81], v[146:149], v[208:211], v[78:81]
	v_mfma_f32_16x16x32_bf16 v[74:77], v[160:163], v[208:211], v[74:77]
	v_mfma_f32_16x16x32_bf16 v[126:129], v[156:159], v[188:191], v[126:129]
	v_mfma_f32_16x16x32_bf16 v[122:125], v[164:167], v[188:191], v[122:125]
	v_mfma_f32_16x16x32_bf16 v[110:113], v[156:159], v[196:199], v[110:113]
	v_mfma_f32_16x16x32_bf16 v[106:109], v[164:167], v[196:199], v[106:109]
	v_mfma_f32_16x16x32_bf16 v[94:97], v[156:159], v[204:207], v[94:97]
	v_mfma_f32_16x16x32_bf16 v[90:93], v[164:167], v[204:207], v[90:93]
	v_mfma_f32_16x16x32_bf16 v[78:81], v[156:159], v[212:215], v[78:81]
	v_mfma_f32_16x16x32_bf16 v[74:77], v[164:167], v[212:215], v[74:77]
	v_mfma_f32_16x16x32_bf16 v[118:121], v[168:171], v[184:187], v[118:121]
	v_mfma_f32_16x16x32_bf16 v[114:117], v[176:179], v[184:187], v[114:117]
	v_mfma_f32_16x16x32_bf16 v[102:105], v[168:171], v[192:195], v[102:105]
	v_mfma_f32_16x16x32_bf16 v[98:101], v[176:179], v[192:195], v[98:101]
	v_mfma_f32_16x16x32_bf16 v[86:89], v[168:171], v[200:203], v[86:89]
	v_mfma_f32_16x16x32_bf16 v[82:85], v[176:179], v[200:203], v[82:85]
	v_mfma_f32_16x16x32_bf16 v[70:73], v[168:171], v[208:211], v[70:73]
	v_mfma_f32_16x16x32_bf16 v[66:69], v[176:179], v[208:211], v[66:69]
	v_mfma_f32_16x16x32_bf16 v[118:121], v[172:175], v[188:191], v[118:121]
	v_mfma_f32_16x16x32_bf16 v[114:117], v[180:183], v[188:191], v[114:117]
	v_mfma_f32_16x16x32_bf16 v[102:105], v[172:175], v[196:199], v[102:105]
	v_mfma_f32_16x16x32_bf16 v[98:101], v[180:183], v[196:199], v[98:101]
	v_mfma_f32_16x16x32_bf16 v[86:89], v[172:175], v[204:207], v[86:89]
	v_mfma_f32_16x16x32_bf16 v[82:85], v[180:183], v[204:207], v[82:85]
	v_mfma_f32_16x16x32_bf16 v[70:73], v[172:175], v[212:215], v[70:73]
	v_mfma_f32_16x16x32_bf16 v[66:69], v[180:183], v[212:215], v[66:69]
	s_setprio 0
	s_barrier
; #define PG8_STAGE(bufoff, gbase, voff) do { _Pragma("unroll") for (int _i = 0; _i < 2; ++_i) \
;         __builtin_amdgcn_global_load_lds((const unsigned*)((const char*)(gbase) + (voff)[_i]), (PG8_LAS unsigned*)(lds + (bufoff) + ldsw + _i * 8192), 16, 0, 0); } while (0)
; #define PG8_LDA(dst, b, h) do { _Pragma("unroll") for (int m = 0; m < 4; ++m) _Pragma("unroll") for (int k = 0; k < 2; ++k) dst[m][k] = *(const PG8_LAS bf16x8*)(lds + PG8_SA(b, h) + aoff + m * 2048 + k * 1024); } while (0)
; #define PG8_MMA(ai, bj, At, Bt) do { __builtin_amdgcn_s_setprio(1); _Pragma("unroll") for (int m = 0; m < 4; ++m) _Pragma("unroll") for (int n = 0; n < 2; ++n) _Pragma("unroll") for (int k = 0; k < 2; ++k) \
;         acc[ai][bj][m][n] = __builtin_amdgcn_mfma_f32_16x16x32_bf16(Bt[n][k], At[m][k], acc[ai][bj][m][n], 0, 0, 0); __builtin_amdgcn_s_setprio(0); } while (0)
; #define PG8_WAIT_V(n) asm volatile("s_waitcnt vmcnt(" #n ")" ::: "memory")
; #define PG8_WAIT_L(n) asm volatile("s_waitcnt lgkmcnt(" #n ")" ::: "memory")
; #define PG8_BAR __builtin_amdgcn_s_barrier()
; #define PG8_SCHED __builtin_amdgcn_sched_barrier(0)
; template <class Epi, class Sched, bool ALIGN_EPI = false, bool SP2 = false>
; __device__ __forceinline__ void gemm_phase(PG8_LAS unsigned char* lds, const Gemm g, const Sched& S, const Epi& E) {
;     ...
;             PG8_LDA(At, 1, 1); PG8_STAGE(PG8_SB(1, 0), b3, voffB); PG8_STAGE(PG8_SB(1, 1), b3 + hstep, voffB); PG8_STAGE(PG8_SA(1, 0), a3, voffA);
;             PG8_WAIT_V(8); PG8_WAIT_L(0); PG8_BAR; PG8_MMA(1, 0, At, B0); PG8_MMA(1, 1, At, B1); PG8_BAR; PG8_SCHED;
;     ...
;         }
;         if constexpr (ALIGN_EPI) { if (wr == 0) PG8_BAR; }
	s_add_i32 s40, s55, s33
	v_lshl_add_u64 v[218:219], v[218:219], 0, s[18:19]
	s_mov_b32 m0, s40
	ds_read_b128 v[184:187], v154 offset:49152
	ds_read_b128 v[188:191], v154 offset:50176
	ds_read_b128 v[192:195], v154 offset:51200
	ds_read_b128 v[196:199], v154 offset:52224
	ds_read_b128 v[200:203], v154 offset:53248
	ds_read_b128 v[204:207], v154 offset:54272
	ds_read_b128 v[208:211], v154 offset:55296
	ds_read_b128 v[212:215], v154 offset:56320
	global_load_lds_dwordx4 v[218:219], off
	s_add_i32 m0, s40, 0x2000
	s_add_u32 s38, s38, 0x400080
	v_lshl_add_u64 v[218:219], v[220:221], 0, s[18:19]
	s_addc_u32 s39, s39, 0
	s_add_i32 s40, s56, s33
	global_load_lds_dwordx4 v[218:219], off
	v_lshl_add_u64 v[218:219], s[38:39], 0, v[132:133]
	s_mov_b32 m0, s40
	s_nop 0
	global_load_lds_dwordx4 v[218:219], off
	v_lshl_add_u64 v[218:219], s[38:39], 0, v[136:137]
	s_add_i32 m0, s40, 0x2000
	s_nop 0
	global_load_lds_dwordx4 v[218:219], off
	v_lshl_add_u64 v[218:219], v[222:223], 0, s[18:19]
	s_mov_b32 m0, s48
	s_nop 0
	global_load_lds_dwordx4 v[218:219], off
	v_lshl_add_u64 v[218:219], v[224:225], 0, s[18:19]
	s_mov_b32 m0, s49
	s_nop 0
	global_load_lds_dwordx4 v[218:219], off
	s_waitcnt vmcnt(8)
	s_waitcnt lgkmcnt(0)
	s_barrier
	s_setprio 1
	s_waitcnt lgkmcnt(0)
	v_mfma_f32_16x16x32_bf16 v[62:65], v[146:149], v[184:187], v[62:65]
	v_mfma_f32_16x16x32_bf16 v[58:61], v[160:163], v[184:187], v[58:61]
	v_mfma_f32_16x16x32_bf16 v[46:49], v[146:149], v[192:195], v[46:49]
	v_mfma_f32_16x16x32_bf16 v[42:45], v[160:163], v[192:195], v[42:45]
	v_mfma_f32_16x16x32_bf16 v[30:33], v[146:149], v[200:203], v[30:33]
	v_mfma_f32_16x16x32_bf16 v[26:29], v[160:163], v[200:203], v[26:29]
	v_mfma_f32_16x16x32_bf16 v[14:17], v[146:149], v[208:211], v[14:17]
	v_mfma_f32_16x16x32_bf16 v[10:13], v[160:163], v[208:211], v[10:13]
	v_mfma_f32_16x16x32_bf16 v[62:65], v[156:159], v[188:191], v[62:65]
	v_mfma_f32_16x16x32_bf16 v[58:61], v[164:167], v[188:191], v[58:61]
	v_mfma_f32_16x16x32_bf16 v[46:49], v[156:159], v[196:199], v[46:49]
	v_mfma_f32_16x16x32_bf16 v[42:45], v[164:167], v[196:199], v[42:45]
	v_mfma_f32_16x16x32_bf16 v[30:33], v[156:159], v[204:207], v[30:33]
	v_mfma_f32_16x16x32_bf16 v[26:29], v[164:167], v[204:207], v[26:29]
	v_mfma_f32_16x16x32_bf16 v[14:17], v[156:159], v[212:215], v[14:17]
	v_mfma_f32_16x16x32_bf16 v[10:13], v[164:167], v[212:215], v[10:13]
	v_mfma_f32_16x16x32_bf16 v[54:57], v[168:171], v[184:187], v[54:57]
	v_mfma_f32_16x16x32_bf16 v[50:53], v[176:179], v[184:187], v[50:53]
	v_mfma_f32_16x16x32_bf16 v[38:41], v[168:171], v[192:195], v[38:41]
	v_mfma_f32_16x16x32_bf16 v[34:37], v[176:179], v[192:195], v[34:37]
	v_mfma_f32_16x16x32_bf16 v[22:25], v[168:171], v[200:203], v[22:25]
	v_mfma_f32_16x16x32_bf16 v[18:21], v[176:179], v[200:203], v[18:21]
	v_mfma_f32_16x16x32_bf16 v[6:9], v[168:171], v[208:211], v[6:9]
	v_mfma_f32_16x16x32_bf16 v[2:5], v[176:179], v[208:211], v[2:5]
	v_mfma_f32_16x16x32_bf16 v[54:57], v[172:175], v[188:191], v[54:57]
	v_mfma_f32_16x16x32_bf16 v[50:53], v[180:183], v[188:191], v[50:53]
	v_mfma_f32_16x16x32_bf16 v[38:41], v[172:175], v[196:199], v[38:41]
	v_mfma_f32_16x16x32_bf16 v[34:37], v[180:183], v[196:199], v[34:37]
	v_mfma_f32_16x16x32_bf16 v[22:25], v[172:175], v[204:207], v[22:25]
	v_mfma_f32_16x16x32_bf16 v[18:21], v[180:183], v[204:207], v[18:21]
	v_mfma_f32_16x16x32_bf16 v[6:9], v[172:175], v[212:215], v[6:9]
	v_mfma_f32_16x16x32_bf16 v[2:5], v[180:183], v[212:215], v[2:5]
	s_setprio 0
	s_barrier
	s_add_i32 s54, s54, 2
	s_add_u32 s36, s36, 0x100
	s_addc_u32 s37, s37, 0
	s_add_u32 s52, s52, 0x100
	s_addc_u32 s53, s53, 0
	s_cmpk_gt_u32 s54, 0xfd
	s_cbranch_scc0 .LBB0_1089
	s_and_b64 vcc, exec, s[20:21]
	s_cbranch_vccz .LBB0_1092
	s_barrier
